# attention loop: cost-weighted VALU spacing around MFMAs (transcendental 5/3, DMA gaps lighter)
# baseline (speedup 1.0000x reference)
; #define SBAR() __builtin_amdgcn_sched_barrier(0)
; #define PK4N(PV, BASE, OUT) do { u32x4 w_ = {cvtpk(PV[BASE + 0], PV[BASE + 1]), cvtpk(PV[BASE + 2], PV[BASE + 3]), \
;     cvtpk(PV[BASE + 4], PV[BASE + 5]), cvtpk(PV[BASE + 6], PV[BASE + 7])}; OUT = *reinterpret_cast<bf16x8*>(&w_); } while (0)
; #define MAPSTEP(QKT, MC, L, PA0, PA1, PA2, PA3) do { f32x16 p0, p1; \
;     QKT; \
;     sm_fixed(p0, p1, MC, L, PA0, PA1, PA2, PA3); } while (0)
; __device__ __forceinline__ void sm_fixed(f32x16& p0, f32x16& p1, float mC, float& l_reg, bf16x8& pa0, bf16x8& pa1, bf16x8& pa2, bf16x8& pa3) {
;   constexpr float C = 1.4426950408889634f;
; #pragma unroll
;   for (int r = 0; r < 16; ++r) p0[r] = __builtin_amdgcn_exp2f(fmaf(p0[r], C, -mC));
; #pragma unroll
;   for (int r = 0; r < 16; ++r) p1[r] = __builtin_amdgcn_exp2f(fmaf(p1[r], C, -mC));
;   float ps = 0;
; #pragma unroll
;   for (int r = 0; r < 16; ++r) ps += p0[r];
; #pragma unroll
;   for (int r = 0; r < 16; ++r) ps += p1[r];
;   { auto rr = __builtin_amdgcn_permlane32_swap(__float_as_uint(ps), __float_as_uint(ps), false, false);
;     ps = __uint_as_float(rr[0]) + __uint_as_float(rr[1]); }
;   l_reg += ps;
;     ...
;   PK4N(p0, 0, pa0); PK4N(p0, 8, pa1); PK4N(p1, 0, pa2); PK4N(p1, 8, pa3);
; __device__ __forceinline__ void attn_item(const P& p, int layer, int item, char* lds) {
;     ...
;   for (int j = 0; j < NTILE; ++j) {
;     asm volatile("s_waitcnt vmcnt(0)" ::: "memory"); __syncthreads();
;     if (j + 1 < NTILE) ISSUE_T(j + 1, (j + 1) & 1);
;     const char* S = lds + (j & 1) * STG;
;     const int vb = vb0 + (j & 1) * STG;
;     bf16x8 pa0, pa1, pa2, pa3, pb0, pb1, pb2, pb3;
;     MAPSTEP(att_qkt(p0, p1, S, q1, koff, ksw, hi), mC1, l1, pa0, pa1, pa2, pa3);
;     SBAR();
;     MAPSTEP(att_qkt_p(p0, p1, S + ATT_KB, q2, Qp, koff, ksw, hi), mC2, l2, pb0, pb1, pb2, pb3);
;     SBAR();
;     pv_two<0>(o1[0], o2[0], vb, pa0, pa1, pa2, pa3, pb0, pb1, pb2, pb3); pv_two<1>(o1[1], o2[1], vb, pa0, pa1, pa2, pa3, pb0, pb1, pb2, pb3);
;     pv_two<2>(o1[2], o2[2], vb, pa0, pa1, pa2, pa3, pb0, pb1, pb2, pb3); pv_two<3>(o1[3], o2[3], vb, pa0, pa1, pa2, pa3, pb0, pb1, pb2, pb3);
.Lattn_loop:
	s_waitcnt vmcnt(4)
	s_barrier
	s_waitcnt lgkmcnt(3)
	v_mfma_f32_32x32x16_bf16 v[128:143], v[240:243], v[164:167], 0
	ds_read_b128 v[240:243], v235 offset:8192
	v_fmamk_f32 v144, v144, 0x3fb8aa3b, v233
	v_fmamk_f32 v145, v145, 0x3fb8aa3b, v233
	v_exp_f32_e32 v144, v144
	s_add_u32 m0, s7, 0xc000
	s_nop 0
	global_load_lds_dwordx4 v249, s[98:99]
	s_waitcnt lgkmcnt(3)
	v_mfma_f32_32x32x16_bf16 v[128:143], v[244:247], v[160:163], v[128:143]
	ds_read_b128 v[244:247], v230 offset:4096
	v_exp_f32_e32 v145, v145
	v_add_f32_e32 v204, v204, v144
	v_add_f32_e32 v204, v204, v145
	s_add_u32 m0, s7, 0xd000
	s_add_u32 s18, s98, 0x16000
	s_addc_u32 s19, s99, 0
	global_load_lds_dwordx4 v249, s[18:19]
	s_waitcnt lgkmcnt(2)
	v_mfma_f32_32x32x16_bf16 v[128:143], v[218:221], v[210:213], v[128:143]
	ds_read_b64_tr_b16 v[218:219], v234 offset:0
	ds_read_b64_tr_b16 v[220:221], v234 offset:2048
	ds_read_b64_tr_b16 v[210:211], v234 offset:512
	ds_read_b64_tr_b16 v[212:213], v234 offset:2560
	v_cvt_pk_bf16_f32 v192, v144, v145
	v_fmamk_f32 v146, v146, 0x3fb8aa3b, v233
	v_fmamk_f32 v147, v147, 0x3fb8aa3b, v233
	s_add_u32 m0, s7, 0xe000
	s_add_u32 s18, s98, 0x2c000
	s_addc_u32 s19, s99, 0
	global_load_lds_dwordx4 v249, s[18:19]
	s_waitcnt lgkmcnt(4)
	v_mfma_f32_32x32x16_bf16 v[128:143], v[240:243], v[244:247], v[128:143]
	ds_read_b64_tr_b16 v[240:241], v234 offset:1024
	ds_read_b64_tr_b16 v[242:243], v234 offset:3072
	ds_read_b64_tr_b16 v[244:245], v234 offset:1536
	ds_read_b64_tr_b16 v[246:247], v234 offset:3584
	v_exp_f32_e32 v146, v146
	v_exp_f32_e32 v147, v147
	v_add_f32_e32 v204, v204, v146
	s_add_u32 m0, s7, 0xf000
	s_add_u32 s18, s98, 0x42000
	s_addc_u32 s19, s99, 0
	global_load_lds_dwordx4 v249, s[18:19]
	s_add_u32 s98, s98, 0x58000
	s_addc_u32 s99, s99, 0
	s_waitcnt lgkmcnt(6)
	v_mfma_f32_32x32x16_bf16 v[64:79], v[184:187], v[218:221], v[64:79]
	ds_read_b64_tr_b16 v[218:219], v234 offset:4096
	ds_read_b64_tr_b16 v[220:221], v234 offset:6144
	v_add_f32_e32 v204, v204, v147
	v_cvt_pk_bf16_f32 v193, v146, v147
	v_fmamk_f32 v148, v148, 0x3fb8aa3b, v233
	v_fmamk_f32 v149, v149, 0x3fb8aa3b, v233
	v_exp_f32_e32 v148, v148
	s_waitcnt lgkmcnt(6)
	v_mfma_f32_32x32x16_bf16 v[80:95], v[184:187], v[210:213], v[80:95]
	ds_read_b64_tr_b16 v[210:211], v234 offset:4608
	ds_read_b64_tr_b16 v[212:213], v234 offset:6656
	v_exp_f32_e32 v149, v149
	v_add_f32_e32 v204, v204, v148
	v_add_f32_e32 v204, v204, v149
	v_cvt_pk_bf16_f32 v194, v148, v149
	v_fmamk_f32 v150, v150, 0x3fb8aa3b, v233
	v_fmamk_f32 v151, v151, 0x3fb8aa3b, v233
	s_waitcnt lgkmcnt(6)
	v_mfma_f32_32x32x16_bf16 v[96:111], v[184:187], v[240:243], v[96:111]
	ds_read_b64_tr_b16 v[240:241], v234 offset:5120
	ds_read_b64_tr_b16 v[242:243], v234 offset:7168
	v_exp_f32_e32 v150, v150
	v_exp_f32_e32 v151, v151
	v_add_f32_e32 v204, v204, v150
	v_add_f32_e32 v204, v204, v151
	v_cvt_pk_bf16_f32 v195, v150, v151
	v_fmamk_f32 v152, v152, 0x3fb8aa3b, v233
	s_waitcnt lgkmcnt(6)
	v_mfma_f32_32x32x16_bf16 v[112:127], v[184:187], v[244:247], v[112:127]
	ds_read_b64_tr_b16 v[244:245], v234 offset:5632
	ds_read_b64_tr_b16 v[246:247], v234 offset:7680
	v_fmamk_f32 v153, v153, 0x3fb8aa3b, v233
	v_exp_f32_e32 v152, v152
	v_exp_f32_e32 v153, v153
	v_add_f32_e32 v204, v204, v152
	v_add_f32_e32 v204, v204, v153
	s_waitcnt lgkmcnt(6)
	v_mfma_f32_32x32x16_bf16 v[64:79], v[188:191], v[218:221], v[64:79]
	ds_read_b64_tr_b16 v[218:219], v234 offset:8192
	ds_read_b64_tr_b16 v[220:221], v234 offset:10240
	v_cvt_pk_bf16_f32 v196, v152, v153
	v_fmamk_f32 v154, v154, 0x3fb8aa3b, v233
	v_fmamk_f32 v155, v155, 0x3fb8aa3b, v233
	v_exp_f32_e32 v154, v154
	v_exp_f32_e32 v155, v155
	s_waitcnt lgkmcnt(6)
	v_mfma_f32_32x32x16_bf16 v[80:95], v[188:191], v[210:213], v[80:95]
	ds_read_b64_tr_b16 v[210:211], v234 offset:8704
	ds_read_b64_tr_b16 v[212:213], v234 offset:10752
	v_add_f32_e32 v204, v204, v154
	v_add_f32_e32 v204, v204, v155
	v_cvt_pk_bf16_f32 v197, v154, v155
	v_fmamk_f32 v156, v156, 0x3fb8aa3b, v233
	v_fmamk_f32 v157, v157, 0x3fb8aa3b, v233
	v_exp_f32_e32 v156, v156
	s_waitcnt lgkmcnt(6)
	v_mfma_f32_32x32x16_bf16 v[96:111], v[188:191], v[240:243], v[96:111]
	ds_read_b64_tr_b16 v[240:241], v234 offset:9216
	ds_read_b64_tr_b16 v[242:243], v234 offset:11264
	v_exp_f32_e32 v157, v157
	v_add_f32_e32 v204, v204, v156
	v_add_f32_e32 v204, v204, v157
	v_cvt_pk_bf16_f32 v198, v156, v157
	v_fmamk_f32 v158, v158, 0x3fb8aa3b, v233
	v_fmamk_f32 v159, v159, 0x3fb8aa3b, v233
	s_waitcnt lgkmcnt(6)
	v_mfma_f32_32x32x16_bf16 v[112:127], v[188:191], v[244:247], v[112:127]
	ds_read_b64_tr_b16 v[244:245], v234 offset:9728
	ds_read_b64_tr_b16 v[246:247], v234 offset:11776
	v_exp_f32_e32 v158, v158
	v_exp_f32_e32 v159, v159
	v_add_f32_e32 v204, v204, v158
	v_add_f32_e32 v204, v204, v159
	v_cvt_pk_bf16_f32 v199, v158, v159
	s_waitcnt lgkmcnt(6)
	v_mfma_f32_32x32x16_bf16 v[64:79], v[192:195], v[218:221], v[64:79]
	ds_read_b128 v[218:221], v239 offset:12288
	v_fmamk_f32 v128, v128, 0x3fb8aa3b, v231
	v_fmamk_f32 v129, v129, 0x3fb8aa3b, v231
	v_exp_f32_e32 v128, v128
	v_exp_f32_e32 v129, v129
	s_waitcnt lgkmcnt(5)
	v_mfma_f32_32x32x16_bf16 v[80:95], v[192:195], v[210:213], v[80:95]
	ds_read_b128 v[210:213], v238 offset:12288
	v_add_f32_e32 v205, v205, v128
	v_add_f32_e32 v205, v205, v129
	v_cvt_pk_bf16_f32 v184, v128, v129
	v_fmamk_f32 v130, v130, 0x3fb8aa3b, v231
	v_fmamk_f32 v131, v131, 0x3fb8aa3b, v231
	s_waitcnt lgkmcnt(4)
	v_mfma_f32_32x32x16_bf16 v[96:111], v[192:195], v[240:243], v[96:111]
	ds_read_b128 v[240:243], v237 offset:12288
	v_exp_f32_e32 v130, v130
	v_exp_f32_e32 v131, v131
	v_add_f32_e32 v205, v205, v130
	v_add_f32_e32 v205, v205, v131
	v_cvt_pk_bf16_f32 v185, v130, v131
	s_waitcnt lgkmcnt(3)
; #define SBAR() __builtin_amdgcn_sched_barrier(0)
; #define PK4N(PV, BASE, OUT) do { u32x4 w_ = {cvtpk(PV[BASE + 0], PV[BASE + 1]), cvtpk(PV[BASE + 2], PV[BASE + 3]), \
;     cvtpk(PV[BASE + 4], PV[BASE + 5]), cvtpk(PV[BASE + 6], PV[BASE + 7])}; OUT = *reinterpret_cast<bf16x8*>(&w_); } while (0)
; #define MAPSTEP(QKT, MC, L, PA0, PA1, PA2, PA3) do { f32x16 p0, p1; \
;     QKT; \
;     sm_fixed(p0, p1, MC, L, PA0, PA1, PA2, PA3); } while (0)
; __device__ __forceinline__ void sm_fixed(f32x16& p0, f32x16& p1, float mC, float& l_reg, bf16x8& pa0, bf16x8& pa1, bf16x8& pa2, bf16x8& pa3) {
;   constexpr float C = 1.4426950408889634f;
; #pragma unroll
;   for (int r = 0; r < 16; ++r) p0[r] = __builtin_amdgcn_exp2f(fmaf(p0[r], C, -mC));
; #pragma unroll
;   for (int r = 0; r < 16; ++r) p1[r] = __builtin_amdgcn_exp2f(fmaf(p1[r], C, -mC));
;   float ps = 0;
; #pragma unroll
;   for (int r = 0; r < 16; ++r) ps += p0[r];
; #pragma unroll
;   for (int r = 0; r < 16; ++r) ps += p1[r];
;   { auto rr = __builtin_amdgcn_permlane32_swap(__float_as_uint(ps), __float_as_uint(ps), false, false);
;     ps = __uint_as_float(rr[0]) + __uint_as_float(rr[1]); }
;   l_reg += ps;
;     ...
;   PK4N(p0, 0, pa0); PK4N(p0, 8, pa1); PK4N(p1, 0, pa2); PK4N(p1, 8, pa3);
; __device__ __forceinline__ void attn_item(const P& p, int layer, int item, char* lds) {
;     ...
;   for (int j = 0; j < NTILE; ++j) {
;     asm volatile("s_waitcnt vmcnt(0)" ::: "memory"); __syncthreads();
;     if (j + 1 < NTILE) ISSUE_T(j + 1, (j + 1) & 1);
;     const char* S = lds + (j & 1) * STG;
;     const int vb = vb0 + (j & 1) * STG;
;     bf16x8 pa0, pa1, pa2, pa3, pb0, pb1, pb2, pb3;
;     MAPSTEP(att_qkt(p0, p1, S, q1, koff, ksw, hi), mC1, l1, pa0, pa1, pa2, pa3);
;     SBAR();
;     MAPSTEP(att_qkt_p(p0, p1, S + ATT_KB, q2, Qp, koff, ksw, hi), mC2, l2, pb0, pb1, pb2, pb3);
;     SBAR();
;     pv_two<0>(o1[0], o2[0], vb, pa0, pa1, pa2, pa3, pb0, pb1, pb2, pb3); pv_two<1>(o1[1], o2[1], vb, pa0, pa1, pa2, pa3, pb0, pb1, pb2, pb3);
;     pv_two<2>(o1[2], o2[2], vb, pa0, pa1, pa2, pa3, pb0, pb1, pb2, pb3); pv_two<3>(o1[3], o2[3], vb, pa0, pa1, pa2, pa3, pb0, pb1, pb2, pb3);
	v_mfma_f32_32x32x16_bf16 v[112:127], v[192:195], v[244:247], v[112:127]
	ds_read_b128 v[244:247], v230 offset:0
	v_fmamk_f32 v132, v132, 0x3fb8aa3b, v231
	v_fmamk_f32 v133, v133, 0x3fb8aa3b, v231
	v_exp_f32_e32 v132, v132
	v_exp_f32_e32 v133, v133
	s_waitcnt lgkmcnt(3)
	v_mfma_f32_32x32x16_bf16 v[144:159], v[218:221], v[164:167], 0
	ds_read_b128 v[218:221], v235 offset:12288
	v_add_f32_e32 v205, v205, v132
	v_add_f32_e32 v205, v205, v133
	v_cvt_pk_bf16_f32 v186, v132, v133
	v_fmamk_f32 v134, v134, 0x3fb8aa3b, v231
	v_fmamk_f32 v135, v135, 0x3fb8aa3b, v231
	s_waitcnt lgkmcnt(3)
	v_mfma_f32_32x32x16_bf16 v[144:159], v[210:213], v[160:163], v[144:159]
	ds_read_b128 v[210:213], v230 offset:4096
	v_exp_f32_e32 v134, v134
	v_exp_f32_e32 v135, v135
	v_add_f32_e32 v205, v205, v134
	v_add_f32_e32 v205, v205, v135
	v_cvt_pk_bf16_f32 v187, v134, v135
	s_waitcnt lgkmcnt(2)
	v_mfma_f32_32x32x16_bf16 v[144:159], v[240:243], v[244:247], v[144:159]
	ds_read_b64_tr_b16 v[240:241], v234 offset:12288
	ds_read_b64_tr_b16 v[242:243], v234 offset:14336
	ds_read_b64_tr_b16 v[244:245], v234 offset:12800
	ds_read_b64_tr_b16 v[246:247], v234 offset:14848
	v_fmamk_f32 v136, v136, 0x3fb8aa3b, v231
	v_fmamk_f32 v137, v137, 0x3fb8aa3b, v231
	v_exp_f32_e32 v136, v136
	v_exp_f32_e32 v137, v137
	s_waitcnt lgkmcnt(4)
	v_mfma_f32_32x32x16_bf16 v[144:159], v[218:221], v[210:213], v[144:159]
	ds_read_b64_tr_b16 v[218:219], v234 offset:13312
	ds_read_b64_tr_b16 v[220:221], v234 offset:15360
	ds_read_b64_tr_b16 v[210:211], v234 offset:13824
	ds_read_b64_tr_b16 v[212:213], v234 offset:15872
	v_add_f32_e32 v205, v205, v136
	v_add_f32_e32 v205, v205, v137
	v_cvt_pk_bf16_f32 v188, v136, v137
	v_fmamk_f32 v138, v138, 0x3fb8aa3b, v231
	v_fmamk_f32 v139, v139, 0x3fb8aa3b, v231
	s_waitcnt lgkmcnt(6)
	v_mfma_f32_32x32x16_bf16 v[64:79], v[196:199], v[240:243], v[64:79]
	ds_read_b64_tr_b16 v[240:241], v234 offset:0
	ds_read_b64_tr_b16 v[242:243], v234 offset:2048
	v_exp_f32_e32 v138, v138
	v_exp_f32_e32 v139, v139
	v_add_f32_e32 v205, v205, v138
	v_add_f32_e32 v205, v205, v139
	v_cvt_pk_bf16_f32 v189, v138, v139
	s_waitcnt lgkmcnt(6)
	v_mfma_f32_32x32x16_bf16 v[80:95], v[196:199], v[244:247], v[80:95]
	ds_read_b64_tr_b16 v[244:245], v234 offset:512
	ds_read_b64_tr_b16 v[246:247], v234 offset:2560
	v_fmamk_f32 v140, v140, 0x3fb8aa3b, v231
	v_fmamk_f32 v141, v141, 0x3fb8aa3b, v231
	v_exp_f32_e32 v140, v140
	v_exp_f32_e32 v141, v141
	s_waitcnt lgkmcnt(6)
	v_mfma_f32_32x32x16_bf16 v[96:111], v[196:199], v[218:221], v[96:111]
	ds_read_b64_tr_b16 v[218:219], v234 offset:1024
	ds_read_b64_tr_b16 v[220:221], v234 offset:3072
	v_add_f32_e32 v205, v205, v140
	v_add_f32_e32 v205, v205, v141
	v_cvt_pk_bf16_f32 v190, v140, v141
	v_fmamk_f32 v142, v142, 0x3fb8aa3b, v231
	v_fmamk_f32 v143, v143, 0x3fb8aa3b, v231
	s_waitcnt lgkmcnt(6)
	v_mfma_f32_32x32x16_bf16 v[112:127], v[196:199], v[210:213], v[112:127]
	ds_read_b64_tr_b16 v[210:211], v234 offset:1536
	ds_read_b64_tr_b16 v[212:213], v234 offset:3584
	v_exp_f32_e32 v142, v142
	v_exp_f32_e32 v143, v143
	v_add_f32_e32 v205, v205, v142
	v_add_f32_e32 v205, v205, v143
	v_cvt_pk_bf16_f32 v191, v142, v143
	s_add_i32 s6, s6, -1
	s_cmp_eq_u32 s6, 0
	s_cbranch_scc1 .Lattn_exit
	s_waitcnt vmcnt(4)
	s_barrier
	s_waitcnt lgkmcnt(6)
	v_mfma_f32_32x32x16_bf16 v[0:15], v[184:187], v[240:243], v[0:15]
	ds_read_b128 v[240:243], v239 offset:32768
	v_fmamk_f32 v144, v144, 0x3fb8aa3b, v231
	v_fmamk_f32 v145, v145, 0x3fb8aa3b, v231
	v_exp_f32_e32 v144, v144
	s_add_u32 m0, s7, 0x0
	s_nop 0
	global_load_lds_dwordx4 v248, s[40:41]
	s_waitcnt lgkmcnt(5)
	v_mfma_f32_32x32x16_bf16 v[16:31], v[184:187], v[244:247], v[16:31]
	ds_read_b128 v[244:247], v238 offset:32768
	v_exp_f32_e32 v145, v145
	v_add_f32_e32 v205, v205, v144
	v_add_f32_e32 v205, v205, v145
	s_add_u32 m0, s7, 0x2000
	s_add_u32 s18, s40, 0x80
	s_addc_u32 s19, s41, 0
	global_load_lds_dwordx4 v248, s[18:19]
	s_waitcnt lgkmcnt(4)
	v_mfma_f32_32x32x16_bf16 v[32:47], v[184:187], v[218:221], v[32:47]
	ds_read_b128 v[218:221], v237 offset:32768
	v_cvt_pk_bf16_f32 v192, v144, v145
	v_fmamk_f32 v146, v146, 0x3fb8aa3b, v231
	v_fmamk_f32 v147, v147, 0x3fb8aa3b, v231
	s_add_u32 m0, s7, 0x1000
	s_add_u32 s18, s40, 0x2c000
	s_addc_u32 s19, s41, 0
	global_load_lds_dwordx4 v248, s[18:19]
	s_waitcnt lgkmcnt(3)
	v_mfma_f32_32x32x16_bf16 v[48:63], v[184:187], v[210:213], v[48:63]
	ds_read_b128 v[210:213], v235 offset:32768
	v_exp_f32_e32 v146, v146
	v_exp_f32_e32 v147, v147
	v_add_f32_e32 v205, v205, v146
	s_add_u32 m0, s7, 0x3000
	s_add_u32 s18, s40, 0x2c080
	s_addc_u32 s19, s41, 0
	global_load_lds_dwordx4 v248, s[18:19]
	s_add_u32 s40, s40, 0x58000
	s_addc_u32 s41, s41, 0
	s_waitcnt lgkmcnt(3)
	v_mfma_f32_32x32x16_bf16 v[128:143], v[240:243], v[180:183], 0
	ds_read_b64_tr_b16 v[240:241], v234 offset:4096
	ds_read_b64_tr_b16 v[242:243], v234 offset:6144
	v_add_f32_e32 v205, v205, v147
	v_cvt_pk_bf16_f32 v193, v146, v147
	v_fmamk_f32 v148, v148, 0x3fb8aa3b, v231
	v_fmamk_f32 v149, v149, 0x3fb8aa3b, v231
	v_exp_f32_e32 v148, v148
	s_waitcnt lgkmcnt(4)
	v_mfma_f32_32x32x16_bf16 v[128:143], v[244:247], v[176:179], v[128:143]
	ds_read_b64_tr_b16 v[244:245], v234 offset:4608
	ds_read_b64_tr_b16 v[246:247], v234 offset:6656
	v_exp_f32_e32 v149, v149
	v_add_f32_e32 v205, v205, v148
	v_add_f32_e32 v205, v205, v149
	v_cvt_pk_bf16_f32 v194, v148, v149
	v_fmamk_f32 v150, v150, 0x3fb8aa3b, v231
	v_fmamk_f32 v151, v151, 0x3fb8aa3b, v231
	s_waitcnt lgkmcnt(5)
; #define SBAR() __builtin_amdgcn_sched_barrier(0)
; #define PK4N(PV, BASE, OUT) do { u32x4 w_ = {cvtpk(PV[BASE + 0], PV[BASE + 1]), cvtpk(PV[BASE + 2], PV[BASE + 3]), \
;     cvtpk(PV[BASE + 4], PV[BASE + 5]), cvtpk(PV[BASE + 6], PV[BASE + 7])}; OUT = *reinterpret_cast<bf16x8*>(&w_); } while (0)
; #define MAPSTEP(QKT, MC, L, PA0, PA1, PA2, PA3) do { f32x16 p0, p1; \
;     QKT; \
;     sm_fixed(p0, p1, MC, L, PA0, PA1, PA2, PA3); } while (0)
; __device__ __forceinline__ void sm_fixed(f32x16& p0, f32x16& p1, float mC, float& l_reg, bf16x8& pa0, bf16x8& pa1, bf16x8& pa2, bf16x8& pa3) {
;   constexpr float C = 1.4426950408889634f;
; #pragma unroll
;   for (int r = 0; r < 16; ++r) p0[r] = __builtin_amdgcn_exp2f(fmaf(p0[r], C, -mC));
; #pragma unroll
;   for (int r = 0; r < 16; ++r) p1[r] = __builtin_amdgcn_exp2f(fmaf(p1[r], C, -mC));
;   float ps = 0;
; #pragma unroll
;   for (int r = 0; r < 16; ++r) ps += p0[r];
; #pragma unroll
;   for (int r = 0; r < 16; ++r) ps += p1[r];
;   { auto rr = __builtin_amdgcn_permlane32_swap(__float_as_uint(ps), __float_as_uint(ps), false, false);
;     ps = __uint_as_float(rr[0]) + __uint_as_float(rr[1]); }
;   l_reg += ps;
;     ...
;   PK4N(p0, 0, pa0); PK4N(p0, 8, pa1); PK4N(p1, 0, pa2); PK4N(p1, 8, pa3);
; __device__ __forceinline__ void attn_item(const P& p, int layer, int item, char* lds) {
;     ...
;   for (int j = 0; j < NTILE; ++j) {
;     asm volatile("s_waitcnt vmcnt(0)" ::: "memory"); __syncthreads();
;     if (j + 1 < NTILE) ISSUE_T(j + 1, (j + 1) & 1);
;     const char* S = lds + (j & 1) * STG;
;     const int vb = vb0 + (j & 1) * STG;
;     bf16x8 pa0, pa1, pa2, pa3, pb0, pb1, pb2, pb3;
;     MAPSTEP(att_qkt(p0, p1, S, q1, koff, ksw, hi), mC1, l1, pa0, pa1, pa2, pa3);
;     SBAR();
;     MAPSTEP(att_qkt_p(p0, p1, S + ATT_KB, q2, Qp, koff, ksw, hi), mC2, l2, pb0, pb1, pb2, pb3);
;     SBAR();
;     pv_two<0>(o1[0], o2[0], vb, pa0, pa1, pa2, pa3, pb0, pb1, pb2, pb3); pv_two<1>(o1[1], o2[1], vb, pa0, pa1, pa2, pa3, pb0, pb1, pb2, pb3);
;     pv_two<2>(o1[2], o2[2], vb, pa0, pa1, pa2, pa3, pb0, pb1, pb2, pb3); pv_two<3>(o1[3], o2[3], vb, pa0, pa1, pa2, pa3, pb0, pb1, pb2, pb3);
	v_mfma_f32_32x32x16_bf16 v[128:143], v[218:221], v[172:175], v[128:143]
	ds_read_b64_tr_b16 v[218:219], v234 offset:5120
	ds_read_b64_tr_b16 v[220:221], v234 offset:7168
	v_exp_f32_e32 v150, v150
	v_exp_f32_e32 v151, v151
	v_add_f32_e32 v205, v205, v150
	v_add_f32_e32 v205, v205, v151
	v_cvt_pk_bf16_f32 v195, v150, v151
	v_fmamk_f32 v152, v152, 0x3fb8aa3b, v231
	s_waitcnt lgkmcnt(6)
	v_mfma_f32_32x32x16_bf16 v[128:143], v[210:213], v[168:171], v[128:143]
	ds_read_b64_tr_b16 v[210:211], v234 offset:5632
	ds_read_b64_tr_b16 v[212:213], v234 offset:7680
	v_fmamk_f32 v153, v153, 0x3fb8aa3b, v231
	v_exp_f32_e32 v152, v152
	v_exp_f32_e32 v153, v153
	v_add_f32_e32 v205, v205, v152
	v_add_f32_e32 v205, v205, v153
	s_waitcnt lgkmcnt(6)
	v_mfma_f32_32x32x16_bf16 v[0:15], v[188:191], v[240:243], v[0:15]
	ds_read_b64_tr_b16 v[240:241], v234 offset:8192
	ds_read_b64_tr_b16 v[242:243], v234 offset:10240
	v_cvt_pk_bf16_f32 v196, v152, v153
	v_fmamk_f32 v154, v154, 0x3fb8aa3b, v231
	v_fmamk_f32 v155, v155, 0x3fb8aa3b, v231
	v_exp_f32_e32 v154, v154
	v_exp_f32_e32 v155, v155
	s_waitcnt lgkmcnt(6)
	v_mfma_f32_32x32x16_bf16 v[16:31], v[188:191], v[244:247], v[16:31]
	ds_read_b64_tr_b16 v[244:245], v234 offset:8704
	ds_read_b64_tr_b16 v[246:247], v234 offset:10752
	v_add_f32_e32 v205, v205, v154
	v_add_f32_e32 v205, v205, v155
	v_cvt_pk_bf16_f32 v197, v154, v155
	v_fmamk_f32 v156, v156, 0x3fb8aa3b, v231
	v_fmamk_f32 v157, v157, 0x3fb8aa3b, v231
	v_exp_f32_e32 v156, v156
	s_waitcnt lgkmcnt(6)
	v_mfma_f32_32x32x16_bf16 v[32:47], v[188:191], v[218:221], v[32:47]
	ds_read_b64_tr_b16 v[218:219], v234 offset:9216
	ds_read_b64_tr_b16 v[220:221], v234 offset:11264
	v_exp_f32_e32 v157, v157
	v_add_f32_e32 v205, v205, v156
	v_add_f32_e32 v205, v205, v157
	v_cvt_pk_bf16_f32 v198, v156, v157
	v_fmamk_f32 v158, v158, 0x3fb8aa3b, v231
	v_fmamk_f32 v159, v159, 0x3fb8aa3b, v231
	s_waitcnt lgkmcnt(6)
	v_mfma_f32_32x32x16_bf16 v[48:63], v[188:191], v[210:213], v[48:63]
	ds_read_b64_tr_b16 v[210:211], v234 offset:9728
	ds_read_b64_tr_b16 v[212:213], v234 offset:11776
	v_exp_f32_e32 v158, v158
	v_exp_f32_e32 v159, v159
	v_add_f32_e32 v205, v205, v158
	v_add_f32_e32 v205, v205, v159
	v_cvt_pk_bf16_f32 v199, v158, v159
	s_waitcnt lgkmcnt(6)
	v_mfma_f32_32x32x16_bf16 v[0:15], v[192:195], v[240:243], v[0:15]
	ds_read_b128 v[240:243], v239 offset:36864
	v_fmamk_f32 v128, v128, 0x3fb8aa3b, v233
	v_fmamk_f32 v129, v129, 0x3fb8aa3b, v233
	v_exp_f32_e32 v128, v128
	v_exp_f32_e32 v129, v129
	s_waitcnt lgkmcnt(5)
	v_mfma_f32_32x32x16_bf16 v[16:31], v[192:195], v[244:247], v[16:31]
	ds_read_b128 v[244:247], v238 offset:36864
	v_add_f32_e32 v204, v204, v128
	v_add_f32_e32 v204, v204, v129
	v_cvt_pk_bf16_f32 v184, v128, v129
	v_fmamk_f32 v130, v130, 0x3fb8aa3b, v233
	v_fmamk_f32 v131, v131, 0x3fb8aa3b, v233
	s_waitcnt lgkmcnt(4)
	v_mfma_f32_32x32x16_bf16 v[32:47], v[192:195], v[218:221], v[32:47]
	ds_read_b128 v[218:221], v237 offset:36864
	v_exp_f32_e32 v130, v130
	v_exp_f32_e32 v131, v131
	v_add_f32_e32 v204, v204, v130
	v_add_f32_e32 v204, v204, v131
	v_cvt_pk_bf16_f32 v185, v130, v131
	s_waitcnt lgkmcnt(3)
	v_mfma_f32_32x32x16_bf16 v[48:63], v[192:195], v[210:213], v[48:63]
	ds_read_b128 v[210:213], v235 offset:36864
	v_fmamk_f32 v132, v132, 0x3fb8aa3b, v233
	v_fmamk_f32 v133, v133, 0x3fb8aa3b, v233
	v_exp_f32_e32 v132, v132
	v_exp_f32_e32 v133, v133
	s_waitcnt lgkmcnt(3)
	v_mfma_f32_32x32x16_bf16 v[144:159], v[240:243], v[180:183], 0
	ds_read_b64_tr_b16 v[240:241], v234 offset:12288
	ds_read_b64_tr_b16 v[242:243], v234 offset:14336
	v_add_f32_e32 v204, v204, v132
	v_add_f32_e32 v204, v204, v133
	v_cvt_pk_bf16_f32 v186, v132, v133
	v_fmamk_f32 v134, v134, 0x3fb8aa3b, v233
	v_fmamk_f32 v135, v135, 0x3fb8aa3b, v233
	s_waitcnt lgkmcnt(4)
	v_mfma_f32_32x32x16_bf16 v[144:159], v[244:247], v[176:179], v[144:159]
	ds_read_b64_tr_b16 v[244:245], v234 offset:12800
	ds_read_b64_tr_b16 v[246:247], v234 offset:14848
	v_exp_f32_e32 v134, v134
	v_exp_f32_e32 v135, v135
	v_add_f32_e32 v204, v204, v134
	v_add_f32_e32 v204, v204, v135
	v_cvt_pk_bf16_f32 v187, v134, v135
	s_waitcnt lgkmcnt(5)
	v_mfma_f32_32x32x16_bf16 v[144:159], v[218:221], v[172:175], v[144:159]
	ds_read_b64_tr_b16 v[218:219], v234 offset:13312
	ds_read_b64_tr_b16 v[220:221], v234 offset:15360
	v_fmamk_f32 v136, v136, 0x3fb8aa3b, v233
	v_fmamk_f32 v137, v137, 0x3fb8aa3b, v233
	v_exp_f32_e32 v136, v136
	v_exp_f32_e32 v137, v137
	s_waitcnt lgkmcnt(6)
	v_mfma_f32_32x32x16_bf16 v[144:159], v[210:213], v[168:171], v[144:159]
	ds_read_b64_tr_b16 v[210:211], v234 offset:13824
	ds_read_b64_tr_b16 v[212:213], v234 offset:15872
	v_add_f32_e32 v204, v204, v136
	v_add_f32_e32 v204, v204, v137
	v_cvt_pk_bf16_f32 v188, v136, v137
	v_fmamk_f32 v138, v138, 0x3fb8aa3b, v233
	v_fmamk_f32 v139, v139, 0x3fb8aa3b, v233
	s_waitcnt lgkmcnt(6)
	v_mfma_f32_32x32x16_bf16 v[0:15], v[196:199], v[240:243], v[0:15]
	ds_read_b128 v[240:243], v239 offset:40960
	v_exp_f32_e32 v138, v138
	v_exp_f32_e32 v139, v139
	v_add_f32_e32 v204, v204, v138
	v_add_f32_e32 v204, v204, v139
	v_cvt_pk_bf16_f32 v189, v138, v139
	s_waitcnt lgkmcnt(5)
	v_mfma_f32_32x32x16_bf16 v[16:31], v[196:199], v[244:247], v[16:31]
	ds_read_b128 v[244:247], v238 offset:40960
	v_fmamk_f32 v140, v140, 0x3fb8aa3b, v233
	v_fmamk_f32 v141, v141, 0x3fb8aa3b, v233
	v_exp_f32_e32 v140, v140
	v_exp_f32_e32 v141, v141
	s_waitcnt lgkmcnt(4)
	v_mfma_f32_32x32x16_bf16 v[32:47], v[196:199], v[218:221], v[32:47]
	ds_read_b128 v[218:221], v237 offset:40960
	v_add_f32_e32 v204, v204, v140
	v_add_f32_e32 v204, v204, v141
	v_cvt_pk_bf16_f32 v190, v140, v141
	v_fmamk_f32 v142, v142, 0x3fb8aa3b, v233
	v_fmamk_f32 v143, v143, 0x3fb8aa3b, v233
	s_waitcnt lgkmcnt(3)
	v_mfma_f32_32x32x16_bf16 v[48:63], v[196:199], v[210:213], v[48:63]
	ds_read_b128 v[210:213], v230 offset:0
	v_exp_f32_e32 v142, v142
	v_exp_f32_e32 v143, v143
	v_add_f32_e32 v204, v204, v142
	v_add_f32_e32 v204, v204, v143
	v_cvt_pk_bf16_f32 v191, v142, v143
	s_waitcnt vmcnt(4)
	s_barrier
; #define SBAR() __builtin_amdgcn_sched_barrier(0)
; #define PK4N(PV, BASE, OUT) do { u32x4 w_ = {cvtpk(PV[BASE + 0], PV[BASE + 1]), cvtpk(PV[BASE + 2], PV[BASE + 3]), \
;     cvtpk(PV[BASE + 4], PV[BASE + 5]), cvtpk(PV[BASE + 6], PV[BASE + 7])}; OUT = *reinterpret_cast<bf16x8*>(&w_); } while (0)
; #define MAPSTEP(QKT, MC, L, PA0, PA1, PA2, PA3) do { f32x16 p0, p1; \
;     QKT; \
;     sm_fixed(p0, p1, MC, L, PA0, PA1, PA2, PA3); } while (0)
; __device__ __forceinline__ void sm_fixed(f32x16& p0, f32x16& p1, float mC, float& l_reg, bf16x8& pa0, bf16x8& pa1, bf16x8& pa2, bf16x8& pa3) {
;   constexpr float C = 1.4426950408889634f;
; #pragma unroll
;   for (int r = 0; r < 16; ++r) p0[r] = __builtin_amdgcn_exp2f(fmaf(p0[r], C, -mC));
; #pragma unroll
;   for (int r = 0; r < 16; ++r) p1[r] = __builtin_amdgcn_exp2f(fmaf(p1[r], C, -mC));
;   float ps = 0;
; #pragma unroll
;   for (int r = 0; r < 16; ++r) ps += p0[r];
; #pragma unroll
;   for (int r = 0; r < 16; ++r) ps += p1[r];
;   { auto rr = __builtin_amdgcn_permlane32_swap(__float_as_uint(ps), __float_as_uint(ps), false, false);
;     ps = __uint_as_float(rr[0]) + __uint_as_float(rr[1]); }
;   l_reg += ps;
;     ...
;   PK4N(p0, 0, pa0); PK4N(p0, 8, pa1); PK4N(p1, 0, pa2); PK4N(p1, 8, pa3);
; __device__ __forceinline__ void attn_item(const P& p, int layer, int item, char* lds) {
;     ...
;   for (int j = 0; j < NTILE; ++j) {
;     asm volatile("s_waitcnt vmcnt(0)" ::: "memory"); __syncthreads();
;     if (j + 1 < NTILE) ISSUE_T(j + 1, (j + 1) & 1);
;     const char* S = lds + (j & 1) * STG;
;     const int vb = vb0 + (j & 1) * STG;
;     bf16x8 pa0, pa1, pa2, pa3, pb0, pb1, pb2, pb3;
;     MAPSTEP(att_qkt(p0, p1, S, q1, koff, ksw, hi), mC1, l1, pa0, pa1, pa2, pa3);
;     SBAR();
;     MAPSTEP(att_qkt_p(p0, p1, S + ATT_KB, q2, Qp, koff, ksw, hi), mC2, l2, pb0, pb1, pb2, pb3);
;     SBAR();
;     pv_two<0>(o1[0], o2[0], vb, pa0, pa1, pa2, pa3, pb0, pb1, pb2, pb3); pv_two<1>(o1[1], o2[1], vb, pa0, pa1, pa2, pa3, pb0, pb1, pb2, pb3);
;     pv_two<2>(o1[2], o2[2], vb, pa0, pa1, pa2, pa3, pb0, pb1, pb2, pb3); pv_two<3>(o1[3], o2[3], vb, pa0, pa1, pa2, pa3, pb0, pb1, pb2, pb3);
	s_waitcnt lgkmcnt(3)
	v_mfma_f32_32x32x16_bf16 v[128:143], v[240:243], v[164:167], 0
	ds_read_b128 v[240:243], v235 offset:40960
	v_fmamk_f32 v144, v144, 0x3fb8aa3b, v233
	v_fmamk_f32 v145, v145, 0x3fb8aa3b, v233
	v_exp_f32_e32 v144, v144
	s_add_u32 m0, s7, 0x4000
	s_nop 0
	global_load_lds_dwordx4 v249, s[98:99]
	s_waitcnt lgkmcnt(3)
	v_mfma_f32_32x32x16_bf16 v[128:143], v[244:247], v[160:163], v[128:143]
	ds_read_b128 v[244:247], v230 offset:4096
	v_exp_f32_e32 v145, v145
	v_add_f32_e32 v204, v204, v144
	v_add_f32_e32 v204, v204, v145
	s_add_u32 m0, s7, 0x5000
	s_add_u32 s18, s98, 0x16000
	s_addc_u32 s19, s99, 0
	global_load_lds_dwordx4 v249, s[18:19]
	s_waitcnt lgkmcnt(2)
	v_mfma_f32_32x32x16_bf16 v[128:143], v[218:221], v[210:213], v[128:143]
	ds_read_b64_tr_b16 v[218:219], v234 offset:32768
	ds_read_b64_tr_b16 v[220:221], v234 offset:34816
	ds_read_b64_tr_b16 v[210:211], v234 offset:33280
	ds_read_b64_tr_b16 v[212:213], v234 offset:35328
	v_cvt_pk_bf16_f32 v192, v144, v145
	v_fmamk_f32 v146, v146, 0x3fb8aa3b, v233
	v_fmamk_f32 v147, v147, 0x3fb8aa3b, v233
	s_add_u32 m0, s7, 0x6000
	s_add_u32 s18, s98, 0x2c000
	s_addc_u32 s19, s99, 0
	global_load_lds_dwordx4 v249, s[18:19]
	s_waitcnt lgkmcnt(4)
	v_mfma_f32_32x32x16_bf16 v[128:143], v[240:243], v[244:247], v[128:143]
	ds_read_b64_tr_b16 v[240:241], v234 offset:33792
	ds_read_b64_tr_b16 v[242:243], v234 offset:35840
	ds_read_b64_tr_b16 v[244:245], v234 offset:34304
	ds_read_b64_tr_b16 v[246:247], v234 offset:36352
	v_exp_f32_e32 v146, v146
	v_exp_f32_e32 v147, v147
	v_add_f32_e32 v204, v204, v146
	s_add_u32 m0, s7, 0x7000
	s_add_u32 s18, s98, 0x42000
	s_addc_u32 s19, s99, 0
	global_load_lds_dwordx4 v249, s[18:19]
	s_add_u32 s98, s98, 0x58000
	s_addc_u32 s99, s99, 0
	s_waitcnt lgkmcnt(6)
	v_mfma_f32_32x32x16_bf16 v[64:79], v[184:187], v[218:221], v[64:79]
	ds_read_b64_tr_b16 v[218:219], v234 offset:36864
	ds_read_b64_tr_b16 v[220:221], v234 offset:38912
	v_add_f32_e32 v204, v204, v147
	v_cvt_pk_bf16_f32 v193, v146, v147
	v_fmamk_f32 v148, v148, 0x3fb8aa3b, v233
	v_fmamk_f32 v149, v149, 0x3fb8aa3b, v233
	v_exp_f32_e32 v148, v148
	s_waitcnt lgkmcnt(6)
	v_mfma_f32_32x32x16_bf16 v[80:95], v[184:187], v[210:213], v[80:95]
	ds_read_b64_tr_b16 v[210:211], v234 offset:37376
	ds_read_b64_tr_b16 v[212:213], v234 offset:39424
	v_exp_f32_e32 v149, v149
	v_add_f32_e32 v204, v204, v148
	v_add_f32_e32 v204, v204, v149
	v_cvt_pk_bf16_f32 v194, v148, v149
	v_fmamk_f32 v150, v150, 0x3fb8aa3b, v233
	v_fmamk_f32 v151, v151, 0x3fb8aa3b, v233
	s_waitcnt lgkmcnt(6)
	v_mfma_f32_32x32x16_bf16 v[96:111], v[184:187], v[240:243], v[96:111]
	ds_read_b64_tr_b16 v[240:241], v234 offset:37888
	ds_read_b64_tr_b16 v[242:243], v234 offset:39936
	v_exp_f32_e32 v150, v150
	v_exp_f32_e32 v151, v151
	v_add_f32_e32 v204, v204, v150
	v_add_f32_e32 v204, v204, v151
	v_cvt_pk_bf16_f32 v195, v150, v151
	v_fmamk_f32 v152, v152, 0x3fb8aa3b, v233
	s_waitcnt lgkmcnt(6)
	v_mfma_f32_32x32x16_bf16 v[112:127], v[184:187], v[244:247], v[112:127]
	ds_read_b64_tr_b16 v[244:245], v234 offset:38400
	ds_read_b64_tr_b16 v[246:247], v234 offset:40448
	v_fmamk_f32 v153, v153, 0x3fb8aa3b, v233
	v_exp_f32_e32 v152, v152
	v_exp_f32_e32 v153, v153
	v_add_f32_e32 v204, v204, v152
	v_add_f32_e32 v204, v204, v153
	s_waitcnt lgkmcnt(6)
	v_mfma_f32_32x32x16_bf16 v[64:79], v[188:191], v[218:221], v[64:79]
	ds_read_b64_tr_b16 v[218:219], v234 offset:40960
	ds_read_b64_tr_b16 v[220:221], v234 offset:43008
	v_cvt_pk_bf16_f32 v196, v152, v153
	v_fmamk_f32 v154, v154, 0x3fb8aa3b, v233
	v_fmamk_f32 v155, v155, 0x3fb8aa3b, v233
	v_exp_f32_e32 v154, v154
	v_exp_f32_e32 v155, v155
	s_waitcnt lgkmcnt(6)
	v_mfma_f32_32x32x16_bf16 v[80:95], v[188:191], v[210:213], v[80:95]
	ds_read_b64_tr_b16 v[210:211], v234 offset:41472
	ds_read_b64_tr_b16 v[212:213], v234 offset:43520
	v_add_f32_e32 v204, v204, v154
	v_add_f32_e32 v204, v204, v155
	v_cvt_pk_bf16_f32 v197, v154, v155
	v_fmamk_f32 v156, v156, 0x3fb8aa3b, v233
	v_fmamk_f32 v157, v157, 0x3fb8aa3b, v233
	v_exp_f32_e32 v156, v156
	s_waitcnt lgkmcnt(6)
	v_mfma_f32_32x32x16_bf16 v[96:111], v[188:191], v[240:243], v[96:111]
	ds_read_b64_tr_b16 v[240:241], v234 offset:41984
	ds_read_b64_tr_b16 v[242:243], v234 offset:44032
	v_exp_f32_e32 v157, v157
	v_add_f32_e32 v204, v204, v156
	v_add_f32_e32 v204, v204, v157
	v_cvt_pk_bf16_f32 v198, v156, v157
	v_fmamk_f32 v158, v158, 0x3fb8aa3b, v233
	v_fmamk_f32 v159, v159, 0x3fb8aa3b, v233
	s_waitcnt lgkmcnt(6)
	v_mfma_f32_32x32x16_bf16 v[112:127], v[188:191], v[244:247], v[112:127]
	ds_read_b64_tr_b16 v[244:245], v234 offset:42496
	ds_read_b64_tr_b16 v[246:247], v234 offset:44544
	v_exp_f32_e32 v158, v158
	v_exp_f32_e32 v159, v159
	v_add_f32_e32 v204, v204, v158
	v_add_f32_e32 v204, v204, v159
	v_cvt_pk_bf16_f32 v199, v158, v159
	s_waitcnt lgkmcnt(6)
	v_mfma_f32_32x32x16_bf16 v[64:79], v[192:195], v[218:221], v[64:79]
	ds_read_b128 v[218:221], v239 offset:45056
	v_fmamk_f32 v128, v128, 0x3fb8aa3b, v231
	v_fmamk_f32 v129, v129, 0x3fb8aa3b, v231
	v_exp_f32_e32 v128, v128
	v_exp_f32_e32 v129, v129
	s_waitcnt lgkmcnt(5)
	v_mfma_f32_32x32x16_bf16 v[80:95], v[192:195], v[210:213], v[80:95]
	ds_read_b128 v[210:213], v238 offset:45056
	v_add_f32_e32 v205, v205, v128
	v_add_f32_e32 v205, v205, v129
	v_cvt_pk_bf16_f32 v184, v128, v129
	v_fmamk_f32 v130, v130, 0x3fb8aa3b, v231
	v_fmamk_f32 v131, v131, 0x3fb8aa3b, v231
	s_waitcnt lgkmcnt(4)
	v_mfma_f32_32x32x16_bf16 v[96:111], v[192:195], v[240:243], v[96:111]
	ds_read_b128 v[240:243], v237 offset:45056
	v_exp_f32_e32 v130, v130
	v_exp_f32_e32 v131, v131
	v_add_f32_e32 v205, v205, v130
	v_add_f32_e32 v205, v205, v131
	v_cvt_pk_bf16_f32 v185, v130, v131
	s_waitcnt lgkmcnt(3)
; #define SBAR() __builtin_amdgcn_sched_barrier(0)
; #define PK4N(PV, BASE, OUT) do { u32x4 w_ = {cvtpk(PV[BASE + 0], PV[BASE + 1]), cvtpk(PV[BASE + 2], PV[BASE + 3]), \
;     cvtpk(PV[BASE + 4], PV[BASE + 5]), cvtpk(PV[BASE + 6], PV[BASE + 7])}; OUT = *reinterpret_cast<bf16x8*>(&w_); } while (0)
; #define MAPSTEP(QKT, MC, L, PA0, PA1, PA2, PA3) do { f32x16 p0, p1; \
;     QKT; \
;     sm_fixed(p0, p1, MC, L, PA0, PA1, PA2, PA3); } while (0)
; __device__ __forceinline__ void sm_fixed(f32x16& p0, f32x16& p1, float mC, float& l_reg, bf16x8& pa0, bf16x8& pa1, bf16x8& pa2, bf16x8& pa3) {
;   constexpr float C = 1.4426950408889634f;
; #pragma unroll
;   for (int r = 0; r < 16; ++r) p0[r] = __builtin_amdgcn_exp2f(fmaf(p0[r], C, -mC));
; #pragma unroll
;   for (int r = 0; r < 16; ++r) p1[r] = __builtin_amdgcn_exp2f(fmaf(p1[r], C, -mC));
;   float ps = 0;
; #pragma unroll
;   for (int r = 0; r < 16; ++r) ps += p0[r];
; #pragma unroll
;   for (int r = 0; r < 16; ++r) ps += p1[r];
;   { auto rr = __builtin_amdgcn_permlane32_swap(__float_as_uint(ps), __float_as_uint(ps), false, false);
;     ps = __uint_as_float(rr[0]) + __uint_as_float(rr[1]); }
;   l_reg += ps;
;     ...
;   PK4N(p0, 0, pa0); PK4N(p0, 8, pa1); PK4N(p1, 0, pa2); PK4N(p1, 8, pa3);
; __device__ __forceinline__ void attn_item(const P& p, int layer, int item, char* lds) {
;     ...
;   for (int j = 0; j < NTILE; ++j) {
;     asm volatile("s_waitcnt vmcnt(0)" ::: "memory"); __syncthreads();
;     if (j + 1 < NTILE) ISSUE_T(j + 1, (j + 1) & 1);
;     const char* S = lds + (j & 1) * STG;
;     const int vb = vb0 + (j & 1) * STG;
;     bf16x8 pa0, pa1, pa2, pa3, pb0, pb1, pb2, pb3;
;     MAPSTEP(att_qkt(p0, p1, S, q1, koff, ksw, hi), mC1, l1, pa0, pa1, pa2, pa3);
;     SBAR();
;     MAPSTEP(att_qkt_p(p0, p1, S + ATT_KB, q2, Qp, koff, ksw, hi), mC2, l2, pb0, pb1, pb2, pb3);
;     SBAR();
;     pv_two<0>(o1[0], o2[0], vb, pa0, pa1, pa2, pa3, pb0, pb1, pb2, pb3); pv_two<1>(o1[1], o2[1], vb, pa0, pa1, pa2, pa3, pb0, pb1, pb2, pb3);
;     pv_two<2>(o1[2], o2[2], vb, pa0, pa1, pa2, pa3, pb0, pb1, pb2, pb3); pv_two<3>(o1[3], o2[3], vb, pa0, pa1, pa2, pa3, pb0, pb1, pb2, pb3);
	v_mfma_f32_32x32x16_bf16 v[112:127], v[192:195], v[244:247], v[112:127]
	ds_read_b128 v[244:247], v230 offset:0
	v_fmamk_f32 v132, v132, 0x3fb8aa3b, v231
	v_fmamk_f32 v133, v133, 0x3fb8aa3b, v231
	v_exp_f32_e32 v132, v132
	v_exp_f32_e32 v133, v133
	s_waitcnt lgkmcnt(3)
	v_mfma_f32_32x32x16_bf16 v[144:159], v[218:221], v[164:167], 0
	ds_read_b128 v[218:221], v235 offset:45056
	v_add_f32_e32 v205, v205, v132
	v_add_f32_e32 v205, v205, v133
	v_cvt_pk_bf16_f32 v186, v132, v133
	v_fmamk_f32 v134, v134, 0x3fb8aa3b, v231
	v_fmamk_f32 v135, v135, 0x3fb8aa3b, v231
	s_waitcnt lgkmcnt(3)
	v_mfma_f32_32x32x16_bf16 v[144:159], v[210:213], v[160:163], v[144:159]
	ds_read_b128 v[210:213], v230 offset:4096
	v_exp_f32_e32 v134, v134
	v_exp_f32_e32 v135, v135
	v_add_f32_e32 v205, v205, v134
	v_add_f32_e32 v205, v205, v135
	v_cvt_pk_bf16_f32 v187, v134, v135
	s_waitcnt lgkmcnt(2)
	v_mfma_f32_32x32x16_bf16 v[144:159], v[240:243], v[244:247], v[144:159]
	ds_read_b64_tr_b16 v[240:241], v234 offset:45056
	ds_read_b64_tr_b16 v[242:243], v234 offset:47104
	ds_read_b64_tr_b16 v[244:245], v234 offset:45568
	ds_read_b64_tr_b16 v[246:247], v234 offset:47616
	v_fmamk_f32 v136, v136, 0x3fb8aa3b, v231
	v_fmamk_f32 v137, v137, 0x3fb8aa3b, v231
	v_exp_f32_e32 v136, v136
	v_exp_f32_e32 v137, v137
	s_waitcnt lgkmcnt(4)
	v_mfma_f32_32x32x16_bf16 v[144:159], v[218:221], v[210:213], v[144:159]
	ds_read_b64_tr_b16 v[218:219], v234 offset:46080
	ds_read_b64_tr_b16 v[220:221], v234 offset:48128
	ds_read_b64_tr_b16 v[210:211], v234 offset:46592
	ds_read_b64_tr_b16 v[212:213], v234 offset:48640
	v_add_f32_e32 v205, v205, v136
	v_add_f32_e32 v205, v205, v137
	v_cvt_pk_bf16_f32 v188, v136, v137
	v_fmamk_f32 v138, v138, 0x3fb8aa3b, v231
	v_fmamk_f32 v139, v139, 0x3fb8aa3b, v231
	s_waitcnt lgkmcnt(6)
	v_mfma_f32_32x32x16_bf16 v[64:79], v[196:199], v[240:243], v[64:79]
	ds_read_b64_tr_b16 v[240:241], v234 offset:32768
	ds_read_b64_tr_b16 v[242:243], v234 offset:34816
	v_exp_f32_e32 v138, v138
	v_exp_f32_e32 v139, v139
	v_add_f32_e32 v205, v205, v138
	v_add_f32_e32 v205, v205, v139
	v_cvt_pk_bf16_f32 v189, v138, v139
	s_waitcnt lgkmcnt(6)
	v_mfma_f32_32x32x16_bf16 v[80:95], v[196:199], v[244:247], v[80:95]
	ds_read_b64_tr_b16 v[244:245], v234 offset:33280
	ds_read_b64_tr_b16 v[246:247], v234 offset:35328
	v_fmamk_f32 v140, v140, 0x3fb8aa3b, v231
	v_fmamk_f32 v141, v141, 0x3fb8aa3b, v231
	v_exp_f32_e32 v140, v140
	v_exp_f32_e32 v141, v141
	s_waitcnt lgkmcnt(6)
	v_mfma_f32_32x32x16_bf16 v[96:111], v[196:199], v[218:221], v[96:111]
	ds_read_b64_tr_b16 v[218:219], v234 offset:33792
	ds_read_b64_tr_b16 v[220:221], v234 offset:35840
	v_add_f32_e32 v205, v205, v140
	v_add_f32_e32 v205, v205, v141
	v_cvt_pk_bf16_f32 v190, v140, v141
	v_fmamk_f32 v142, v142, 0x3fb8aa3b, v231
	v_fmamk_f32 v143, v143, 0x3fb8aa3b, v231
	s_waitcnt lgkmcnt(6)
	v_mfma_f32_32x32x16_bf16 v[112:127], v[196:199], v[210:213], v[112:127]
	ds_read_b64_tr_b16 v[210:211], v234 offset:34304
	ds_read_b64_tr_b16 v[212:213], v234 offset:36352
	v_exp_f32_e32 v142, v142
	v_exp_f32_e32 v143, v143
	v_add_f32_e32 v205, v205, v142
	v_add_f32_e32 v205, v205, v143
	v_cvt_pk_bf16_f32 v191, v142, v143
	s_waitcnt vmcnt(4)
	s_barrier
	s_waitcnt lgkmcnt(6)
	v_mfma_f32_32x32x16_bf16 v[0:15], v[184:187], v[240:243], v[0:15]
	ds_read_b128 v[240:243], v239 offset:0
	v_fmamk_f32 v144, v144, 0x3fb8aa3b, v231
	v_fmamk_f32 v145, v145, 0x3fb8aa3b, v231
	v_exp_f32_e32 v144, v144
	s_add_u32 m0, s7, 0x8000
	s_nop 0
	global_load_lds_dwordx4 v248, s[40:41]
	s_waitcnt lgkmcnt(5)
	v_mfma_f32_32x32x16_bf16 v[16:31], v[184:187], v[244:247], v[16:31]
	ds_read_b128 v[244:247], v238 offset:0
	v_exp_f32_e32 v145, v145
	v_add_f32_e32 v205, v205, v144
	v_add_f32_e32 v205, v205, v145
	s_add_u32 m0, s7, 0xa000
	s_add_u32 s18, s40, 0x80
	s_addc_u32 s19, s41, 0
	global_load_lds_dwordx4 v248, s[18:19]
	s_waitcnt lgkmcnt(4)
	v_mfma_f32_32x32x16_bf16 v[32:47], v[184:187], v[218:221], v[32:47]
	ds_read_b128 v[218:221], v237 offset:0
	v_cvt_pk_bf16_f32 v192, v144, v145
	v_fmamk_f32 v146, v146, 0x3fb8aa3b, v231
	v_fmamk_f32 v147, v147, 0x3fb8aa3b, v231
	s_add_u32 m0, s7, 0x9000
	s_add_u32 s18, s40, 0x2c000
	s_addc_u32 s19, s41, 0
	global_load_lds_dwordx4 v248, s[18:19]
	s_waitcnt lgkmcnt(3)
	v_mfma_f32_32x32x16_bf16 v[48:63], v[184:187], v[210:213], v[48:63]
	ds_read_b128 v[210:213], v235 offset:0
	v_exp_f32_e32 v146, v146
	v_exp_f32_e32 v147, v147
	v_add_f32_e32 v205, v205, v146
	s_add_u32 m0, s7, 0xb000
	s_add_u32 s18, s40, 0x2c080
	s_addc_u32 s19, s41, 0
	global_load_lds_dwordx4 v248, s[18:19]
	s_add_u32 s40, s40, 0x58000
	s_addc_u32 s41, s41, 0
	s_waitcnt lgkmcnt(3)
	v_mfma_f32_32x32x16_bf16 v[128:143], v[240:243], v[180:183], 0
	ds_read_b64_tr_b16 v[240:241], v234 offset:36864
	ds_read_b64_tr_b16 v[242:243], v234 offset:38912
	v_add_f32_e32 v205, v205, v147
	v_cvt_pk_bf16_f32 v193, v146, v147
	v_fmamk_f32 v148, v148, 0x3fb8aa3b, v231
	v_fmamk_f32 v149, v149, 0x3fb8aa3b, v231
	v_exp_f32_e32 v148, v148
	s_waitcnt lgkmcnt(4)
	v_mfma_f32_32x32x16_bf16 v[128:143], v[244:247], v[176:179], v[128:143]
	ds_read_b64_tr_b16 v[244:245], v234 offset:37376
	ds_read_b64_tr_b16 v[246:247], v234 offset:39424
	v_exp_f32_e32 v149, v149
	v_add_f32_e32 v205, v205, v148
	v_add_f32_e32 v205, v205, v149
	v_cvt_pk_bf16_f32 v194, v148, v149
	v_fmamk_f32 v150, v150, 0x3fb8aa3b, v231
	v_fmamk_f32 v151, v151, 0x3fb8aa3b, v231
	s_waitcnt lgkmcnt(5)
	v_mfma_f32_32x32x16_bf16 v[128:143], v[218:221], v[172:175], v[128:143]
	ds_read_b64_tr_b16 v[218:219], v234 offset:37888
	ds_read_b64_tr_b16 v[220:221], v234 offset:39936
	v_exp_f32_e32 v150, v150
	v_exp_f32_e32 v151, v151
	v_add_f32_e32 v205, v205, v150
	v_add_f32_e32 v205, v205, v151
	v_cvt_pk_bf16_f32 v195, v150, v151
	v_fmamk_f32 v152, v152, 0x3fb8aa3b, v231
	s_waitcnt lgkmcnt(6)
; #define SBAR() __builtin_amdgcn_sched_barrier(0)
; #define PK4N(PV, BASE, OUT) do { u32x4 w_ = {cvtpk(PV[BASE + 0], PV[BASE + 1]), cvtpk(PV[BASE + 2], PV[BASE + 3]), \
;     cvtpk(PV[BASE + 4], PV[BASE + 5]), cvtpk(PV[BASE + 6], PV[BASE + 7])}; OUT = *reinterpret_cast<bf16x8*>(&w_); } while (0)
; #define MAPSTEP(QKT, MC, L, PA0, PA1, PA2, PA3) do { f32x16 p0, p1; \
;     QKT; \
;     sm_fixed(p0, p1, MC, L, PA0, PA1, PA2, PA3); } while (0)
; __device__ __forceinline__ void sm_fixed(f32x16& p0, f32x16& p1, float mC, float& l_reg, bf16x8& pa0, bf16x8& pa1, bf16x8& pa2, bf16x8& pa3) {
;   constexpr float C = 1.4426950408889634f;
; #pragma unroll
;   for (int r = 0; r < 16; ++r) p0[r] = __builtin_amdgcn_exp2f(fmaf(p0[r], C, -mC));
; #pragma unroll
;   for (int r = 0; r < 16; ++r) p1[r] = __builtin_amdgcn_exp2f(fmaf(p1[r], C, -mC));
;   float ps = 0;
; #pragma unroll
;   for (int r = 0; r < 16; ++r) ps += p0[r];
; #pragma unroll
;   for (int r = 0; r < 16; ++r) ps += p1[r];
;   { auto rr = __builtin_amdgcn_permlane32_swap(__float_as_uint(ps), __float_as_uint(ps), false, false);
;     ps = __uint_as_float(rr[0]) + __uint_as_float(rr[1]); }
;   l_reg += ps;
;     ...
;   PK4N(p0, 0, pa0); PK4N(p0, 8, pa1); PK4N(p1, 0, pa2); PK4N(p1, 8, pa3);
; __device__ __forceinline__ void attn_item(const P& p, int layer, int item, char* lds) {
;     ...
;   for (int j = 0; j < NTILE; ++j) {
;     asm volatile("s_waitcnt vmcnt(0)" ::: "memory"); __syncthreads();
;     if (j + 1 < NTILE) ISSUE_T(j + 1, (j + 1) & 1);
;     const char* S = lds + (j & 1) * STG;
;     const int vb = vb0 + (j & 1) * STG;
;     bf16x8 pa0, pa1, pa2, pa3, pb0, pb1, pb2, pb3;
;     MAPSTEP(att_qkt(p0, p1, S, q1, koff, ksw, hi), mC1, l1, pa0, pa1, pa2, pa3);
;     SBAR();
;     MAPSTEP(att_qkt_p(p0, p1, S + ATT_KB, q2, Qp, koff, ksw, hi), mC2, l2, pb0, pb1, pb2, pb3);
;     SBAR();
;     pv_two<0>(o1[0], o2[0], vb, pa0, pa1, pa2, pa3, pb0, pb1, pb2, pb3); pv_two<1>(o1[1], o2[1], vb, pa0, pa1, pa2, pa3, pb0, pb1, pb2, pb3);
;     pv_two<2>(o1[2], o2[2], vb, pa0, pa1, pa2, pa3, pb0, pb1, pb2, pb3); pv_two<3>(o1[3], o2[3], vb, pa0, pa1, pa2, pa3, pb0, pb1, pb2, pb3);
	v_mfma_f32_32x32x16_bf16 v[128:143], v[210:213], v[168:171], v[128:143]
	ds_read_b64_tr_b16 v[210:211], v234 offset:38400
	ds_read_b64_tr_b16 v[212:213], v234 offset:40448
	v_fmamk_f32 v153, v153, 0x3fb8aa3b, v231
	v_exp_f32_e32 v152, v152
	v_exp_f32_e32 v153, v153
	v_add_f32_e32 v205, v205, v152
	v_add_f32_e32 v205, v205, v153
	s_waitcnt lgkmcnt(6)
	v_mfma_f32_32x32x16_bf16 v[0:15], v[188:191], v[240:243], v[0:15]
	ds_read_b64_tr_b16 v[240:241], v234 offset:40960
	ds_read_b64_tr_b16 v[242:243], v234 offset:43008
	v_cvt_pk_bf16_f32 v196, v152, v153
	v_fmamk_f32 v154, v154, 0x3fb8aa3b, v231
	v_fmamk_f32 v155, v155, 0x3fb8aa3b, v231
	v_exp_f32_e32 v154, v154
	v_exp_f32_e32 v155, v155
	s_waitcnt lgkmcnt(6)
	v_mfma_f32_32x32x16_bf16 v[16:31], v[188:191], v[244:247], v[16:31]
	ds_read_b64_tr_b16 v[244:245], v234 offset:41472
	ds_read_b64_tr_b16 v[246:247], v234 offset:43520
	v_add_f32_e32 v205, v205, v154
	v_add_f32_e32 v205, v205, v155
	v_cvt_pk_bf16_f32 v197, v154, v155
	v_fmamk_f32 v156, v156, 0x3fb8aa3b, v231
	v_fmamk_f32 v157, v157, 0x3fb8aa3b, v231
	v_exp_f32_e32 v156, v156
	s_waitcnt lgkmcnt(6)
	v_mfma_f32_32x32x16_bf16 v[32:47], v[188:191], v[218:221], v[32:47]
	ds_read_b64_tr_b16 v[218:219], v234 offset:41984
	ds_read_b64_tr_b16 v[220:221], v234 offset:44032
	v_exp_f32_e32 v157, v157
	v_add_f32_e32 v205, v205, v156
	v_add_f32_e32 v205, v205, v157
	v_cvt_pk_bf16_f32 v198, v156, v157
	v_fmamk_f32 v158, v158, 0x3fb8aa3b, v231
	v_fmamk_f32 v159, v159, 0x3fb8aa3b, v231
	s_waitcnt lgkmcnt(6)
	v_mfma_f32_32x32x16_bf16 v[48:63], v[188:191], v[210:213], v[48:63]
	ds_read_b64_tr_b16 v[210:211], v234 offset:42496
	ds_read_b64_tr_b16 v[212:213], v234 offset:44544
	v_exp_f32_e32 v158, v158
	v_exp_f32_e32 v159, v159
	v_add_f32_e32 v205, v205, v158
	v_add_f32_e32 v205, v205, v159
	v_cvt_pk_bf16_f32 v199, v158, v159
	s_waitcnt lgkmcnt(6)
	v_mfma_f32_32x32x16_bf16 v[0:15], v[192:195], v[240:243], v[0:15]
	ds_read_b128 v[240:243], v239 offset:4096
	v_fmamk_f32 v128, v128, 0x3fb8aa3b, v233
	v_fmamk_f32 v129, v129, 0x3fb8aa3b, v233
	v_exp_f32_e32 v128, v128
	v_exp_f32_e32 v129, v129
	s_waitcnt lgkmcnt(5)
	v_mfma_f32_32x32x16_bf16 v[16:31], v[192:195], v[244:247], v[16:31]
	ds_read_b128 v[244:247], v238 offset:4096
	v_add_f32_e32 v204, v204, v128
	v_add_f32_e32 v204, v204, v129
	v_cvt_pk_bf16_f32 v184, v128, v129
	v_fmamk_f32 v130, v130, 0x3fb8aa3b, v233
	v_fmamk_f32 v131, v131, 0x3fb8aa3b, v233
	s_waitcnt lgkmcnt(4)
	v_mfma_f32_32x32x16_bf16 v[32:47], v[192:195], v[218:221], v[32:47]
	ds_read_b128 v[218:221], v237 offset:4096
	v_exp_f32_e32 v130, v130
	v_exp_f32_e32 v131, v131
	v_add_f32_e32 v204, v204, v130
	v_add_f32_e32 v204, v204, v131
	v_cvt_pk_bf16_f32 v185, v130, v131
	s_waitcnt lgkmcnt(3)
	v_mfma_f32_32x32x16_bf16 v[48:63], v[192:195], v[210:213], v[48:63]
	ds_read_b128 v[210:213], v235 offset:4096
	v_fmamk_f32 v132, v132, 0x3fb8aa3b, v233
	v_fmamk_f32 v133, v133, 0x3fb8aa3b, v233
	v_exp_f32_e32 v132, v132
	v_exp_f32_e32 v133, v133
	s_waitcnt lgkmcnt(3)
	v_mfma_f32_32x32x16_bf16 v[144:159], v[240:243], v[180:183], 0
	ds_read_b64_tr_b16 v[240:241], v234 offset:45056
	ds_read_b64_tr_b16 v[242:243], v234 offset:47104
	v_add_f32_e32 v204, v204, v132
	v_add_f32_e32 v204, v204, v133
	v_cvt_pk_bf16_f32 v186, v132, v133
	v_fmamk_f32 v134, v134, 0x3fb8aa3b, v233
	v_fmamk_f32 v135, v135, 0x3fb8aa3b, v233
	s_waitcnt lgkmcnt(4)
	v_mfma_f32_32x32x16_bf16 v[144:159], v[244:247], v[176:179], v[144:159]
	ds_read_b64_tr_b16 v[244:245], v234 offset:45568
	ds_read_b64_tr_b16 v[246:247], v234 offset:47616
	v_exp_f32_e32 v134, v134
	v_exp_f32_e32 v135, v135
	v_add_f32_e32 v204, v204, v134
	v_add_f32_e32 v204, v204, v135
	v_cvt_pk_bf16_f32 v187, v134, v135
	s_waitcnt lgkmcnt(5)
	v_mfma_f32_32x32x16_bf16 v[144:159], v[218:221], v[172:175], v[144:159]
	ds_read_b64_tr_b16 v[218:219], v234 offset:46080
	ds_read_b64_tr_b16 v[220:221], v234 offset:48128
	v_fmamk_f32 v136, v136, 0x3fb8aa3b, v233
	v_fmamk_f32 v137, v137, 0x3fb8aa3b, v233
	v_exp_f32_e32 v136, v136
	v_exp_f32_e32 v137, v137
	s_waitcnt lgkmcnt(6)
	v_mfma_f32_32x32x16_bf16 v[144:159], v[210:213], v[168:171], v[144:159]
	ds_read_b64_tr_b16 v[210:211], v234 offset:46592
	ds_read_b64_tr_b16 v[212:213], v234 offset:48640
	v_add_f32_e32 v204, v204, v136
	v_add_f32_e32 v204, v204, v137
	v_cvt_pk_bf16_f32 v188, v136, v137
	v_fmamk_f32 v138, v138, 0x3fb8aa3b, v233
	v_fmamk_f32 v139, v139, 0x3fb8aa3b, v233
	s_waitcnt lgkmcnt(6)
	v_mfma_f32_32x32x16_bf16 v[0:15], v[196:199], v[240:243], v[0:15]
	ds_read_b128 v[240:243], v239 offset:8192
	v_exp_f32_e32 v138, v138
	v_exp_f32_e32 v139, v139
	v_add_f32_e32 v204, v204, v138
	v_add_f32_e32 v204, v204, v139
	v_cvt_pk_bf16_f32 v189, v138, v139
	s_waitcnt lgkmcnt(5)
	v_mfma_f32_32x32x16_bf16 v[16:31], v[196:199], v[244:247], v[16:31]
	ds_read_b128 v[244:247], v238 offset:8192
	v_fmamk_f32 v140, v140, 0x3fb8aa3b, v233
	v_fmamk_f32 v141, v141, 0x3fb8aa3b, v233
	v_exp_f32_e32 v140, v140
	v_exp_f32_e32 v141, v141
	s_waitcnt lgkmcnt(4)
	v_mfma_f32_32x32x16_bf16 v[32:47], v[196:199], v[218:221], v[32:47]
	ds_read_b128 v[218:221], v237 offset:8192
	v_add_f32_e32 v204, v204, v140
	v_add_f32_e32 v204, v204, v141
	v_cvt_pk_bf16_f32 v190, v140, v141
	v_fmamk_f32 v142, v142, 0x3fb8aa3b, v233
	v_fmamk_f32 v143, v143, 0x3fb8aa3b, v233
	s_waitcnt lgkmcnt(3)
	v_mfma_f32_32x32x16_bf16 v[48:63], v[196:199], v[210:213], v[48:63]
	ds_read_b128 v[210:213], v230 offset:0
	v_exp_f32_e32 v142, v142
	v_exp_f32_e32 v143, v143
	v_add_f32_e32 v204, v204, v142
	v_add_f32_e32 v204, v204, v143
	v_cvt_pk_bf16_f32 v191, v142, v143
	s_branch .Lattn_loop
; #define SBAR() __builtin_amdgcn_sched_barrier(0)
; #define MFMA(a, b, c) __builtin_amdgcn_mfma_f32_32x32x16_bf16(a, b, c, 0, 0, 0)
; template <int D0> __device__ __forceinline__ void pv_two(f32x16& oa, f32x16& ob, int vb, bf16x8 a0, bf16x8 a1, bf16x8 a2, bf16x8 a3,
;                                                          bf16x8 b0, bf16x8 b1, bf16x8 b2, bf16x8 b3) {
;     ...
;   { const s16x4 l0 = tr_read<v_rd_off(D0, 0, 0)>(vb), h0 = tr_read<v_rd_off(D0, 0, 1)>(vb), l1 = tr_read<v_rd_off(D0, 1, 0)>(vb), h1 = tr_read<v_rd_off(D0, 1, 1)>(vb);
;     asm volatile("s_waitcnt lgkmcnt(0)" ::: "memory"); SBAR();
;     const bf16x8 v0 = PKV(l0, h0), v1 = PKV(l1, h1);
;     oa = MFMA(a0, v0, oa); ob = MFMA(b0, v0, ob); oa = MFMA(a1, v1, oa); ob = MFMA(b1, v1, ob); }
;   { const s16x4 l2 = tr_read<v_rd_off(D0, 2, 0)>(vb), h2 = tr_read<v_rd_off(D0, 2, 1)>(vb), l3 = tr_read<v_rd_off(D0, 3, 0)>(vb), h3 = tr_read<v_rd_off(D0, 3, 1)>(vb);
;     asm volatile("s_waitcnt lgkmcnt(0)" ::: "memory"); SBAR();
;     const bf16x8 v2 = PKV(l2, h2), v3 = PKV(l3, h3);
;     oa = MFMA(a2, v2, oa); ob = MFMA(b2, v2, ob); oa = MFMA(a3, v3, oa); ob = MFMA(b3, v3, ob); }
;     ...
; }
; __device__ __forceinline__ void sm_fixed(f32x16& p0, f32x16& p1, float mC, float& l_reg, bf16x8& pa0, bf16x8& pa1, bf16x8& pa2, bf16x8& pa3) {
;     ...
;   { auto rr = __builtin_amdgcn_permlane32_swap(__float_as_uint(ps), __float_as_uint(ps), false, false);
;     ps = __uint_as_float(rr[0]) + __uint_as_float(rr[1]); }
;   l_reg += ps;
.Lattn_exit:
	s_waitcnt lgkmcnt(6)
	v_mfma_f32_32x32x16_bf16 v[0:15], v[184:187], v[240:243], v[0:15]
	ds_read_b64_tr_b16 v[240:241], v234 offset:4096
	ds_read_b64_tr_b16 v[242:243], v234 offset:6144
	v_fmamk_f32 v144, v144, 0x3fb8aa3b, v231
	v_fmamk_f32 v145, v145, 0x3fb8aa3b, v231
	v_exp_f32_e32 v144, v144
	v_exp_f32_e32 v145, v145
	v_add_f32_e32 v205, v205, v144
	v_add_f32_e32 v205, v205, v145
	v_cvt_pk_bf16_f32 v192, v144, v145
	s_waitcnt lgkmcnt(6)
	v_mfma_f32_32x32x16_bf16 v[16:31], v[184:187], v[244:247], v[16:31]
	ds_read_b64_tr_b16 v[244:245], v234 offset:4608
	ds_read_b64_tr_b16 v[246:247], v234 offset:6656
	v_fmamk_f32 v146, v146, 0x3fb8aa3b, v231
	v_fmamk_f32 v147, v147, 0x3fb8aa3b, v231
	v_exp_f32_e32 v146, v146
	v_exp_f32_e32 v147, v147
	v_add_f32_e32 v205, v205, v146
	v_add_f32_e32 v205, v205, v147
	v_cvt_pk_bf16_f32 v193, v146, v147
	s_waitcnt lgkmcnt(6)
	v_mfma_f32_32x32x16_bf16 v[32:47], v[184:187], v[218:221], v[32:47]
	ds_read_b64_tr_b16 v[218:219], v234 offset:5120
	ds_read_b64_tr_b16 v[220:221], v234 offset:7168
	v_fmamk_f32 v148, v148, 0x3fb8aa3b, v231
	v_fmamk_f32 v149, v149, 0x3fb8aa3b, v231
	v_exp_f32_e32 v148, v148
	v_exp_f32_e32 v149, v149
	v_add_f32_e32 v205, v205, v148
	v_add_f32_e32 v205, v205, v149
	v_cvt_pk_bf16_f32 v194, v148, v149
	s_waitcnt lgkmcnt(6)
	v_mfma_f32_32x32x16_bf16 v[48:63], v[184:187], v[210:213], v[48:63]
	ds_read_b64_tr_b16 v[210:211], v234 offset:5632
	ds_read_b64_tr_b16 v[212:213], v234 offset:7680
	v_fmamk_f32 v150, v150, 0x3fb8aa3b, v231
	v_fmamk_f32 v151, v151, 0x3fb8aa3b, v231
	v_exp_f32_e32 v150, v150
	v_exp_f32_e32 v151, v151
	v_add_f32_e32 v205, v205, v150
	v_add_f32_e32 v205, v205, v151
	v_cvt_pk_bf16_f32 v195, v150, v151
	s_waitcnt lgkmcnt(6)
	v_mfma_f32_32x32x16_bf16 v[0:15], v[188:191], v[240:243], v[0:15]
	ds_read_b64_tr_b16 v[240:241], v234 offset:8192
	ds_read_b64_tr_b16 v[242:243], v234 offset:10240
	v_fmamk_f32 v152, v152, 0x3fb8aa3b, v231
	v_fmamk_f32 v153, v153, 0x3fb8aa3b, v231
	v_exp_f32_e32 v152, v152
	v_exp_f32_e32 v153, v153
	v_add_f32_e32 v205, v205, v152
	v_add_f32_e32 v205, v205, v153
	v_cvt_pk_bf16_f32 v196, v152, v153
	s_waitcnt lgkmcnt(6)
	v_mfma_f32_32x32x16_bf16 v[16:31], v[188:191], v[244:247], v[16:31]
	ds_read_b64_tr_b16 v[244:245], v234 offset:8704
	ds_read_b64_tr_b16 v[246:247], v234 offset:10752
	v_fmamk_f32 v154, v154, 0x3fb8aa3b, v231
	v_fmamk_f32 v155, v155, 0x3fb8aa3b, v231
	v_exp_f32_e32 v154, v154
	v_exp_f32_e32 v155, v155
	v_add_f32_e32 v205, v205, v154
	v_add_f32_e32 v205, v205, v155
	v_cvt_pk_bf16_f32 v197, v154, v155
	s_waitcnt lgkmcnt(6)
	v_mfma_f32_32x32x16_bf16 v[32:47], v[188:191], v[218:221], v[32:47]
	ds_read_b64_tr_b16 v[218:219], v234 offset:9216
	ds_read_b64_tr_b16 v[220:221], v234 offset:11264
	v_fmamk_f32 v156, v156, 0x3fb8aa3b, v231
	v_fmamk_f32 v157, v157, 0x3fb8aa3b, v231
	v_exp_f32_e32 v156, v156
	v_exp_f32_e32 v157, v157
	v_add_f32_e32 v205, v205, v156
	v_add_f32_e32 v205, v205, v157
	v_cvt_pk_bf16_f32 v198, v156, v157
	s_waitcnt lgkmcnt(6)
	v_mfma_f32_32x32x16_bf16 v[48:63], v[188:191], v[210:213], v[48:63]
	ds_read_b64_tr_b16 v[210:211], v234 offset:9728
	ds_read_b64_tr_b16 v[212:213], v234 offset:11776
	v_fmamk_f32 v158, v158, 0x3fb8aa3b, v231
	v_fmamk_f32 v159, v159, 0x3fb8aa3b, v231
	v_exp_f32_e32 v158, v158
	v_exp_f32_e32 v159, v159
	v_add_f32_e32 v205, v205, v158
	v_add_f32_e32 v205, v205, v159
	v_cvt_pk_bf16_f32 v199, v158, v159
	s_waitcnt lgkmcnt(6)
	v_mfma_f32_32x32x16_bf16 v[0:15], v[192:195], v[240:243], v[0:15]
	ds_read_b64_tr_b16 v[240:241], v234 offset:12288
	ds_read_b64_tr_b16 v[242:243], v234 offset:14336
	s_waitcnt lgkmcnt(6)
	v_mfma_f32_32x32x16_bf16 v[16:31], v[192:195], v[244:247], v[16:31]
	ds_read_b64_tr_b16 v[244:245], v234 offset:12800
	ds_read_b64_tr_b16 v[246:247], v234 offset:14848
	s_waitcnt lgkmcnt(6)
	v_mfma_f32_32x32x16_bf16 v[32:47], v[192:195], v[218:221], v[32:47]
	ds_read_b64_tr_b16 v[218:219], v234 offset:13312
	ds_read_b64_tr_b16 v[220:221], v234 offset:15360
	s_waitcnt lgkmcnt(6)
	v_mfma_f32_32x32x16_bf16 v[48:63], v[192:195], v[210:213], v[48:63]
	ds_read_b64_tr_b16 v[210:211], v234 offset:13824
	ds_read_b64_tr_b16 v[212:213], v234 offset:15872
	s_waitcnt lgkmcnt(6)
	v_mfma_f32_32x32x16_bf16 v[0:15], v[196:199], v[240:243], v[0:15]
	s_waitcnt lgkmcnt(4)
	v_mfma_f32_32x32x16_bf16 v[16:31], v[196:199], v[244:247], v[16:31]
	s_waitcnt lgkmcnt(2)
	v_mfma_f32_32x32x16_bf16 v[32:47], v[196:199], v[218:221], v[32:47]
	s_waitcnt lgkmcnt(0)
	v_mfma_f32_32x32x16_bf16 v[48:63], v[196:199], v[210:213], v[48:63]
	v_sub_u32_e32 v239, v239, v236
	v_sub_u32_e32 v238, v238, v236
	v_sub_u32_e32 v237, v237, v236
	v_sub_u32_e32 v235, v235, v236
	v_mov_b32_e32 v210, v204
	v_mov_b32_e32 v212, v204
	v_mov_b32_e32 v211, v205
	v_mov_b32_e32 v213, v205
	s_nop 1
	v_permlane32_swap_b32_e32 v210, v212
	v_permlane32_swap_b32_e32 v211, v213
	s_nop 1
	v_add_f32_e32 v204, v210, v212
	v_add_f32_e32 v205, v211, v213
	s_setprio 0
	s_setprio 0
	v_add_u32_e32 v198, v236, v239
	s_waitcnt vmcnt(0)
	s_waitcnt vmcnt(0)
	s_barrier
; #define MFMA(a, b, c) __builtin_amdgcn_mfma_f32_32x32x16_bf16(a, b, c, 0, 0, 0)
; #define PK4N(PV, BASE, OUT) do { u32x4 w_ = {cvtpk(PV[BASE + 0], PV[BASE + 1]), cvtpk(PV[BASE + 2], PV[BASE + 3]), \
;     cvtpk(PV[BASE + 4], PV[BASE + 5]), cvtpk(PV[BASE + 6], PV[BASE + 7])}; OUT = *reinterpret_cast<bf16x8*>(&w_); } while (0)
; __device__ __forceinline__ void att_qkt(f32x16& p0, f32x16& p1, const char* Kb, const bf16x8 (&qr)[4], int koff, int ksw, int hi) {
;   p0 = f32x16{}; p1 = f32x16{};
; #pragma unroll
;   for (int d0 = 0; d0 < 4; ++d0) {
;     const int co = ((d0 * 2 + hi) ^ ksw) << 4;
;     const bf16x8 b0 = *(const bf16x8*)(Kb + koff + co);
;     const bf16x8 b1 = *(const bf16x8*)(Kb + koff + 4096 + co);
;     p0 = MFMA(b0, qr[d0], p0); p1 = MFMA(b1, qr[d0], p1);
;   }
; }
; __device__ __forceinline__ void sm_fixed(f32x16& p0, f32x16& p1, float mC, float& l_reg, bf16x8& pa0, bf16x8& pa1, bf16x8& pa2, bf16x8& pa3) {
;   constexpr float C = 1.4426950408889634f;
; #pragma unroll
;   for (int r = 0; r < 16; ++r) p0[r] = __builtin_amdgcn_exp2f(fmaf(p0[r], C, -mC));
; #pragma unroll
;   for (int r = 0; r < 16; ++r) p1[r] = __builtin_amdgcn_exp2f(fmaf(p1[r], C, -mC));
;   float ps = 0;
; #pragma unroll
;   for (int r = 0; r < 16; ++r) ps += p0[r];
; #pragma unroll
;   for (int r = 0; r < 16; ++r) ps += p1[r];
;   { auto rr = __builtin_amdgcn_permlane32_swap(__float_as_uint(ps), __float_as_uint(ps), false, false);
;     ps = __uint_as_float(rr[0]) + __uint_as_float(rr[1]); }
;   l_reg += ps;
;     ...
;   PK4N(p0, 0, pa0); PK4N(p0, 8, pa1); PK4N(p1, 0, pa2); PK4N(p1, 8, pa3);
	ds_read_b128 v[128:131], v198 offset:32768
	ds_read_b128 v[132:135], v198 offset:36864
	v_add_u32_e32 v199, v236, v238
	s_waitcnt lgkmcnt(1)
	v_mfma_f32_32x32x16_bf16 v[144:159], v[128:131], v[180:183], 0
	v_add_u32_e32 v206, v236, v237
	ds_read_b128 v[186:189], v199 offset:36864
	v_add_u32_e32 v207, v236, v235
	v_and_b32_e32 v184, 0x3fffffc0, v214
	s_add_i32 s3, 0, 0x10000
	ds_read_b128 v[190:193], v206 offset:36864
	v_lshl_add_u32 v184, v184, 2, s3
	s_waitcnt lgkmcnt(2)
	v_mfma_f32_32x32x16_bf16 v[128:143], v[132:135], v[180:183], 0
	ds_read_b128 v[180:183], v199 offset:32768
	v_add_u32_e32 v185, 0x8000, v234
	ds_read_b128 v[194:197], v207 offset:36864
	s_waitcnt lgkmcnt(1)
	v_mfma_f32_32x32x16_bf16 v[144:159], v[180:183], v[176:179], v[144:159]
	ds_read_b128 v[180:183], v206 offset:32768
	s_waitcnt lgkmcnt(0)
	v_mfma_f32_32x32x16_bf16 v[144:159], v[180:183], v[172:175], v[144:159]
	ds_read_b128 v[180:183], v207 offset:32768
	v_mfma_f32_32x32x16_bf16 v[128:143], v[186:189], v[176:179], v[128:143]
	s_waitcnt lgkmcnt(0)
	v_mfma_f32_32x32x16_bf16 v[144:159], v[180:183], v[168:171], v[144:159]
	v_mfma_f32_32x32x16_bf16 v[128:143], v[190:193], v[172:175], v[128:143]
	s_nop 10
	v_fmamk_f32 v144, v144, 0x3fb8aa3b, v233
	v_fmamk_f32 v145, v145, 0x3fb8aa3b, v233
	v_exp_f32_e32 v144, v144
	v_fmamk_f32 v146, v146, 0x3fb8aa3b, v233
	v_exp_f32_e32 v145, v145
	v_fmamk_f32 v147, v147, 0x3fb8aa3b, v233
	v_exp_f32_e32 v146, v146
	v_fmamk_f32 v148, v148, 0x3fb8aa3b, v233
	v_exp_f32_e32 v147, v147
	v_fmamk_f32 v149, v149, 0x3fb8aa3b, v233
	v_exp_f32_e32 v148, v148
	v_mfma_f32_32x32x16_bf16 v[128:143], v[194:197], v[168:171], v[128:143]
	v_add_f32_e32 v168, 0, v144
	v_fmamk_f32 v150, v150, 0x3fb8aa3b, v233
	v_exp_f32_e32 v149, v149
	v_add_f32_e32 v168, v145, v168
	v_fmamk_f32 v151, v151, 0x3fb8aa3b, v233
	v_exp_f32_e32 v150, v150
	v_add_f32_e32 v168, v146, v168
	v_fmamk_f32 v152, v152, 0x3fb8aa3b, v233
	v_exp_f32_e32 v151, v151
	v_add_f32_e32 v168, v147, v168
	v_exp_f32_e32 v152, v152
	v_fmamk_f32 v153, v153, 0x3fb8aa3b, v233
	v_add_f32_e32 v168, v148, v168
	v_exp_f32_e32 v153, v153
	v_fmamk_f32 v154, v154, 0x3fb8aa3b, v233
	v_add_f32_e32 v168, v149, v168
	v_exp_f32_e32 v154, v154
	v_fmamk_f32 v155, v155, 0x3fb8aa3b, v233
	v_add_f32_e32 v168, v150, v168
	v_exp_f32_e32 v155, v155
	v_fmamk_f32 v156, v156, 0x3fb8aa3b, v233
	v_add_f32_e32 v168, v151, v168
	v_exp_f32_e32 v156, v156
	v_fmamk_f32 v157, v157, 0x3fb8aa3b, v233
	v_add_f32_e32 v168, v152, v168
	v_exp_f32_e32 v157, v157
	v_fmamk_f32 v158, v158, 0x3fb8aa3b, v233
	v_add_f32_e32 v168, v153, v168
	v_exp_f32_e32 v158, v158
	v_fmamk_f32 v159, v159, 0x3fb8aa3b, v233
	v_add_f32_e32 v168, v154, v168
	v_exp_f32_e32 v159, v159
	v_fmamk_f32 v128, v128, 0x3fb8aa3b, v233
	v_add_f32_e32 v168, v155, v168
	v_exp_f32_e32 v128, v128
	v_fmamk_f32 v129, v129, 0x3fb8aa3b, v233
	v_add_f32_e32 v168, v156, v168
	v_exp_f32_e32 v129, v129
	v_fmamk_f32 v130, v130, 0x3fb8aa3b, v233
	v_add_f32_e32 v168, v157, v168
	v_exp_f32_e32 v130, v130
	v_fmamk_f32 v131, v131, 0x3fb8aa3b, v233
	v_add_f32_e32 v168, v158, v168
	v_exp_f32_e32 v131, v131
	v_fmamk_f32 v132, v132, 0x3fb8aa3b, v233
	v_add_f32_e32 v168, v159, v168
	v_exp_f32_e32 v132, v132
	v_fmamk_f32 v133, v133, 0x3fb8aa3b, v233
	v_add_f32_e32 v168, v128, v168
	v_exp_f32_e32 v133, v133
	v_fmamk_f32 v134, v134, 0x3fb8aa3b, v233
	v_add_f32_e32 v168, v129, v168
	v_exp_f32_e32 v134, v134
	v_fmamk_f32 v135, v135, 0x3fb8aa3b, v233
	v_add_f32_e32 v168, v130, v168
	v_exp_f32_e32 v135, v135
	v_fmamk_f32 v136, v136, 0x3fb8aa3b, v233
	v_add_f32_e32 v168, v131, v168
	v_exp_f32_e32 v136, v136
	v_fmamk_f32 v137, v137, 0x3fb8aa3b, v233
	v_add_f32_e32 v168, v132, v168
	v_exp_f32_e32 v137, v137
	v_fmamk_f32 v138, v138, 0x3fb8aa3b, v233
	v_add_f32_e32 v168, v133, v168
	v_exp_f32_e32 v138, v138
	v_fmamk_f32 v139, v139, 0x3fb8aa3b, v233
	v_add_f32_e32 v168, v134, v168
	v_exp_f32_e32 v139, v139
	v_fmamk_f32 v140, v140, 0x3fb8aa3b, v233
	v_add_f32_e32 v168, v135, v168
	v_exp_f32_e32 v140, v140
	v_fmamk_f32 v141, v141, 0x3fb8aa3b, v233
	v_add_f32_e32 v168, v136, v168
	v_exp_f32_e32 v141, v141
	v_fmamk_f32 v142, v142, 0x3fb8aa3b, v233
	v_add_f32_e32 v168, v137, v168
	v_exp_f32_e32 v142, v142
	v_fmac_f32_e32 v233, 0x3fb8aa3b, v143
	v_add_f32_e32 v168, v138, v168
	v_exp_f32_e32 v143, v233
	v_add_f32_e32 v168, v139, v168
	v_add_f32_e32 v168, v140, v168
	v_add_f32_e32 v168, v141, v168
	v_add_f32_e32 v168, v142, v168
	v_add_f32_e32 v186, v143, v168
	v_mov_b32_e32 v187, v186
	s_nop 1
	v_permlane32_swap_b32_e32 v186, v187
	v_cvt_pk_bf16_f32 v176, v144, v145
	v_cvt_pk_bf16_f32 v177, v146, v147
	v_cvt_pk_bf16_f32 v178, v148, v149
	v_cvt_pk_bf16_f32 v179, v150, v151
	v_cvt_pk_bf16_f32 v180, v152, v153
	v_cvt_pk_bf16_f32 v181, v154, v155
	v_cvt_pk_bf16_f32 v182, v156, v157
	v_cvt_pk_bf16_f32 v183, v158, v159
	v_cvt_pk_bf16_f32 v168, v128, v129
	v_cvt_pk_bf16_f32 v169, v130, v131
	v_cvt_pk_bf16_f32 v170, v132, v133
	v_cvt_pk_bf16_f32 v171, v134, v135
	v_cvt_pk_bf16_f32 v172, v136, v137
	v_cvt_pk_bf16_f32 v173, v138, v139
	v_cvt_pk_bf16_f32 v174, v140, v141
	v_cvt_pk_bf16_f32 v175, v142, v143
	ds_read_b128 v[128:131], v198 offset:40960
	ds_read_b128 v[132:135], v198 offset:45056
	s_waitcnt lgkmcnt(1)
	v_mfma_f32_32x32x16_bf16 v[144:159], v[128:131], v[164:167], 0
	s_waitcnt lgkmcnt(0)
	v_mfma_f32_32x32x16_bf16 v[128:143], v[132:135], v[164:167], 0
	ds_read_b128 v[164:167], v199 offset:40960
	ds_read_b128 v[188:191], v199 offset:45056
	s_waitcnt lgkmcnt(0)
	v_mfma_f32_32x32x16_bf16 v[128:143], v[188:191], v[160:163], v[128:143]
	v_mfma_f32_32x32x16_bf16 v[144:159], v[164:167], v[160:163], v[144:159]
	ds_read_b128 v[160:163], v206 offset:40960
	ds_read_b128 v[164:167], v206 offset:45056
	ds_read_b128 v[188:191], v230
	s_waitcnt lgkmcnt(0)
; #define SBAR() __builtin_amdgcn_sched_barrier(0)
; #define MFMA(a, b, c) __builtin_amdgcn_mfma_f32_32x32x16_bf16(a, b, c, 0, 0, 0)
; template <int D0> __device__ __forceinline__ void pv_two(f32x16& oa, f32x16& ob, int vb, bf16x8 a0, bf16x8 a1, bf16x8 a2, bf16x8 a3,
;                                                          bf16x8 b0, bf16x8 b1, bf16x8 b2, bf16x8 b3) {
;     ...
;   { const s16x4 l0 = tr_read<v_rd_off(D0, 0, 0)>(vb), h0 = tr_read<v_rd_off(D0, 0, 1)>(vb), l1 = tr_read<v_rd_off(D0, 1, 0)>(vb), h1 = tr_read<v_rd_off(D0, 1, 1)>(vb);
;     asm volatile("s_waitcnt lgkmcnt(0)" ::: "memory"); SBAR();
;     const bf16x8 v0 = PKV(l0, h0), v1 = PKV(l1, h1);
;     oa = MFMA(a0, v0, oa); ob = MFMA(b0, v0, ob); oa = MFMA(a1, v1, oa); ob = MFMA(b1, v1, ob); }
;   { const s16x4 l2 = tr_read<v_rd_off(D0, 2, 0)>(vb), h2 = tr_read<v_rd_off(D0, 2, 1)>(vb), l3 = tr_read<v_rd_off(D0, 3, 0)>(vb), h3 = tr_read<v_rd_off(D0, 3, 1)>(vb);
;     asm volatile("s_waitcnt lgkmcnt(0)" ::: "memory"); SBAR();
;     const bf16x8 v2 = PKV(l2, h2), v3 = PKV(l3, h3);
;     oa = MFMA(a2, v2, oa); ob = MFMA(b2, v2, ob); oa = MFMA(a3, v3, oa); ob = MFMA(b3, v3, ob); }
;     ...
; }
; __device__ __forceinline__ void att_qkt_p(f32x16& p0, f32x16& p1, const char* Kb, const bf16x8 (&qr)[2], const char* Qp, int koff, int ksw, int hi) {
;   p0 = f32x16{}; p1 = f32x16{};
; #pragma unroll
;   for (int d0 = 0; d0 < 4; ++d0) {
;     const int co = ((d0 * 2 + hi) ^ ksw) << 4;
;     const bf16x8 b0 = *(const bf16x8*)(Kb + koff + co);
;     const bf16x8 b1 = *(const bf16x8*)(Kb + koff + 4096 + co);
;     const bf16x8 qd = d0 < 2 ? qr[d0 & 1] : *(const bf16x8*)(Qp + (d0 - 2) * 4096);
;     p0 = MFMA(b0, qd, p0); p1 = MFMA(b1, qd, p1);
;   }
; }
	v_mfma_f32_32x32x16_bf16 v[128:143], v[164:167], v[188:191], v[128:143]
	v_mfma_f32_32x32x16_bf16 v[144:159], v[160:163], v[188:191], v[144:159]
	ds_read_b128 v[160:163], v207 offset:40960
	ds_read_b128 v[164:167], v207 offset:45056
	ds_read_b128 v[188:191], v230 offset:4096
	s_waitcnt lgkmcnt(0)
	v_mfma_f32_32x32x16_bf16 v[128:143], v[164:167], v[188:191], v[128:143]
	v_mfma_f32_32x32x16_bf16 v[144:159], v[160:163], v[188:191], v[144:159]
	s_nop 10
	v_fmamk_f32 v128, v128, 0x3fb8aa3b, v231
	v_exp_f32_e32 v162, v128
	v_fmamk_f32 v128, v129, 0x3fb8aa3b, v231
	v_exp_f32_e32 v163, v128
	v_fmamk_f32 v128, v130, 0x3fb8aa3b, v231
	v_exp_f32_e32 v164, v128
	v_fmamk_f32 v128, v131, 0x3fb8aa3b, v231
	v_exp_f32_e32 v165, v128
	v_fmamk_f32 v128, v132, 0x3fb8aa3b, v231
	v_exp_f32_e32 v166, v128
	v_fmamk_f32 v128, v133, 0x3fb8aa3b, v231
	v_exp_f32_e32 v167, v128
	v_fmamk_f32 v128, v134, 0x3fb8aa3b, v231
	v_exp_f32_e32 v188, v128
	v_fmamk_f32 v128, v135, 0x3fb8aa3b, v231
	v_exp_f32_e32 v189, v128
	v_fmamk_f32 v128, v136, 0x3fb8aa3b, v231
	v_exp_f32_e32 v190, v128
	v_fmamk_f32 v128, v137, 0x3fb8aa3b, v231
	v_fmamk_f32 v144, v144, 0x3fb8aa3b, v231
	v_exp_f32_e32 v191, v128
	v_fmamk_f32 v128, v138, 0x3fb8aa3b, v231
	v_exp_f32_e32 v160, v144
	v_fmamk_f32 v144, v145, 0x3fb8aa3b, v231
	v_exp_f32_e32 v192, v128
	v_fmamk_f32 v128, v139, 0x3fb8aa3b, v231
	v_exp_f32_e32 v145, v144
	v_fmamk_f32 v144, v146, 0x3fb8aa3b, v231
	v_exp_f32_e32 v193, v128
	v_fmamk_f32 v128, v140, 0x3fb8aa3b, v231
	v_exp_f32_e32 v161, v144
	v_fmamk_f32 v144, v147, 0x3fb8aa3b, v231
	v_exp_f32_e32 v194, v128
	v_fmamk_f32 v128, v141, 0x3fb8aa3b, v231
	v_exp_f32_e32 v147, v144
	v_fmamk_f32 v144, v148, 0x3fb8aa3b, v231
	v_exp_f32_e32 v195, v128
	v_fmamk_f32 v128, v142, 0x3fb8aa3b, v231
	v_exp_f32_e32 v148, v144
	v_fmamk_f32 v144, v149, 0x3fb8aa3b, v231
	v_exp_f32_e32 v196, v128
	v_add_f32_e32 v128, 0, v160
	v_exp_f32_e32 v149, v144
	v_fmamk_f32 v144, v150, 0x3fb8aa3b, v231
	v_add_f32_e32 v128, v145, v128
	v_exp_f32_e32 v150, v144
	v_fmamk_f32 v144, v151, 0x3fb8aa3b, v231
	v_add_f32_e32 v128, v161, v128
	v_exp_f32_e32 v151, v144
	v_fmamk_f32 v144, v152, 0x3fb8aa3b, v231
	v_add_f32_e32 v128, v147, v128
	v_exp_f32_e32 v152, v144
	v_fmamk_f32 v144, v153, 0x3fb8aa3b, v231
	v_add_f32_e32 v128, v148, v128
	v_exp_f32_e32 v153, v144
	v_fmamk_f32 v144, v154, 0x3fb8aa3b, v231
	v_add_f32_e32 v128, v149, v128
	v_exp_f32_e32 v154, v144
	v_fmamk_f32 v144, v155, 0x3fb8aa3b, v231
	v_add_f32_e32 v128, v150, v128
	v_exp_f32_e32 v155, v144
	v_fmamk_f32 v144, v156, 0x3fb8aa3b, v231
	v_add_f32_e32 v128, v151, v128
	v_exp_f32_e32 v156, v144
	v_fmamk_f32 v144, v157, 0x3fb8aa3b, v231
	v_add_f32_e32 v128, v152, v128
	v_exp_f32_e32 v157, v144
	v_fmamk_f32 v144, v158, 0x3fb8aa3b, v231
	v_add_f32_e32 v128, v153, v128
	v_exp_f32_e32 v158, v144
	v_fmamk_f32 v144, v159, 0x3fb8aa3b, v231
	v_add_f32_e32 v128, v154, v128
	v_exp_f32_e32 v159, v144
	v_add_f32_e32 v128, v155, v128
	v_add_f32_e32 v128, v156, v128
	v_add_f32_e32 v128, v157, v128
	v_add_f32_e32 v128, v158, v128
	v_add_f32_e32 v128, v159, v128
	v_add_f32_e32 v128, v162, v128
	v_add_f32_e32 v128, v163, v128
	v_add_f32_e32 v128, v164, v128
	v_add_f32_e32 v128, v165, v128
	v_add_f32_e32 v128, v166, v128
	v_add_f32_e32 v128, v167, v128
	v_add_f32_e32 v128, v188, v128
	v_add_f32_e32 v128, v189, v128
	v_add_f32_e32 v128, v190, v128
	v_add_f32_e32 v128, v191, v128
	v_fmac_f32_e32 v231, 0x3fb8aa3b, v143
	v_add_f32_e32 v128, v192, v128
	v_exp_f32_e32 v143, v231
	v_add_f32_e32 v128, v193, v128
	v_add_f32_e32 v128, v194, v128
	v_add_f32_e32 v128, v195, v128
	v_add_f32_e32 v128, v196, v128
	v_add_f32_e32 v144, v143, v128
	v_mov_b32_e32 v146, v144
	s_nop 1
	v_permlane32_swap_b32_e32 v144, v146
	v_cvt_pk_bf16_f32 v128, v160, v145
	v_cvt_pk_bf16_f32 v129, v161, v147
	v_cvt_pk_bf16_f32 v130, v148, v149
	v_cvt_pk_bf16_f32 v131, v150, v151
	v_cvt_pk_bf16_f32 v132, v152, v153
	v_cvt_pk_bf16_f32 v133, v154, v155
	v_cvt_pk_bf16_f32 v134, v156, v157
	v_cvt_pk_bf16_f32 v135, v158, v159
	v_cvt_pk_bf16_f32 v136, v162, v163
	v_cvt_pk_bf16_f32 v137, v164, v165
	v_cvt_pk_bf16_f32 v138, v166, v167
	v_cvt_pk_bf16_f32 v139, v188, v189
	v_cvt_pk_bf16_f32 v140, v190, v191
	v_cvt_pk_bf16_f32 v141, v192, v193
	v_cvt_pk_bf16_f32 v142, v194, v195
	v_cvt_pk_bf16_f32 v143, v196, v143
	ds_read_b64_tr_b16 v[148:149], v185 offset:0
	ds_read_b64_tr_b16 v[150:151], v185 offset:0x800
	ds_read_b64_tr_b16 v[152:153], v185 offset:0x1000
	ds_read_b64_tr_b16 v[154:155], v185 offset:0x1800
	s_waitcnt lgkmcnt(0)
	s_nop 0
	v_mfma_f32_32x32x16_bf16 v[64:79], v[176:179], v[148:151], v[64:79]
	v_mfma_f32_32x32x16_bf16 v[0:15], v[128:131], v[148:151], v[0:15]
	ds_read_b64_tr_b16 v[148:149], v185 offset:0x2000
	ds_read_b64_tr_b16 v[150:151], v185 offset:0x2800
	v_mfma_f32_32x32x16_bf16 v[64:79], v[180:183], v[152:155], v[64:79]
	v_mfma_f32_32x32x16_bf16 v[0:15], v[132:135], v[152:155], v[0:15]
	ds_read_b64_tr_b16 v[152:153], v185 offset:0x3000
	ds_read_b64_tr_b16 v[154:155], v185 offset:0x3800
	s_waitcnt lgkmcnt(0)
; __device__ __forceinline__ int crow(int r, int hi) { return (r & 3) + 8 * (r >> 2) + 4 * hi; }
; #define SBAR() __builtin_amdgcn_sched_barrier(0)
; #define MFMA(a, b, c) __builtin_amdgcn_mfma_f32_32x32x16_bf16(a, b, c, 0, 0, 0)
; template <int D0> __device__ __forceinline__ void pv_two(f32x16& oa, f32x16& ob, int vb, bf16x8 a0, bf16x8 a1, bf16x8 a2, bf16x8 a3,
;                                                          bf16x8 b0, bf16x8 b1, bf16x8 b2, bf16x8 b3) {
;     ...
;   { const s16x4 l0 = tr_read<v_rd_off(D0, 0, 0)>(vb), h0 = tr_read<v_rd_off(D0, 0, 1)>(vb), l1 = tr_read<v_rd_off(D0, 1, 0)>(vb), h1 = tr_read<v_rd_off(D0, 1, 1)>(vb);
;     asm volatile("s_waitcnt lgkmcnt(0)" ::: "memory"); SBAR();
;     const bf16x8 v0 = PKV(l0, h0), v1 = PKV(l1, h1);
;     oa = MFMA(a0, v0, oa); ob = MFMA(b0, v0, ob); oa = MFMA(a1, v1, oa); ob = MFMA(b1, v1, ob); }
;   { const s16x4 l2 = tr_read<v_rd_off(D0, 2, 0)>(vb), h2 = tr_read<v_rd_off(D0, 2, 1)>(vb), l3 = tr_read<v_rd_off(D0, 3, 0)>(vb), h3 = tr_read<v_rd_off(D0, 3, 1)>(vb);
;     asm volatile("s_waitcnt lgkmcnt(0)" ::: "memory"); SBAR();
;     const bf16x8 v2 = PKV(l2, h2), v3 = PKV(l3, h3);
;     oa = MFMA(a2, v2, oa); ob = MFMA(b2, v2, ob); oa = MFMA(a3, v3, oa); ob = MFMA(b3, v3, ob); }
;     ...
; }
; __device__ __forceinline__ void attn_item(const P& p, int layer, int item, char* lds) {
;     ...
;   float r1[16], r2[16];
;   if (hi == 0) li_l[r32] = l1;
;   asm volatile("s_waitcnt lgkmcnt(0)" ::: "memory");
; #pragma unroll
;   for (int r = 0; r < 16; ++r) r1[r] = 1.f / li_l[crow(r, hi)];
;   asm volatile("s_waitcnt lgkmcnt(0)" ::: "memory");
;   if (hi == 0) li_l[r32] = l2;
	v_mfma_f32_32x32x16_bf16 v[64:79], v[168:171], v[148:151], v[64:79]
	v_mfma_f32_32x32x16_bf16 v[0:15], v[136:139], v[148:151], v[0:15]
	ds_read_b64_tr_b16 v[148:149], v185 offset:0x200
	ds_read_b64_tr_b16 v[150:151], v185 offset:0xa00
	v_mfma_f32_32x32x16_bf16 v[64:79], v[172:175], v[152:155], v[64:79]
	v_mfma_f32_32x32x16_bf16 v[0:15], v[140:143], v[152:155], v[0:15]
	ds_read_b64_tr_b16 v[152:153], v185 offset:0x1200
	ds_read_b64_tr_b16 v[154:155], v185 offset:0x1a00
	s_waitcnt lgkmcnt(0)
	v_mfma_f32_32x32x16_bf16 v[80:95], v[176:179], v[148:151], v[80:95]
	v_mfma_f32_32x32x16_bf16 v[16:31], v[128:131], v[148:151], v[16:31]
	ds_read_b64_tr_b16 v[148:149], v185 offset:0x2200
	ds_read_b64_tr_b16 v[150:151], v185 offset:0x2a00
	v_mfma_f32_32x32x16_bf16 v[80:95], v[180:183], v[152:155], v[80:95]
	v_mfma_f32_32x32x16_bf16 v[16:31], v[132:135], v[152:155], v[16:31]
	ds_read_b64_tr_b16 v[152:153], v185 offset:0x3200
	ds_read_b64_tr_b16 v[154:155], v185 offset:0x3a00
	s_waitcnt lgkmcnt(0)
	v_mfma_f32_32x32x16_bf16 v[80:95], v[168:171], v[148:151], v[80:95]
	v_mfma_f32_32x32x16_bf16 v[16:31], v[136:139], v[148:151], v[16:31]
	ds_read_b64_tr_b16 v[148:149], v185 offset:0x400
	ds_read_b64_tr_b16 v[150:151], v185 offset:0xc00
	v_mfma_f32_32x32x16_bf16 v[80:95], v[172:175], v[152:155], v[80:95]
	v_mfma_f32_32x32x16_bf16 v[16:31], v[140:143], v[152:155], v[16:31]
	ds_read_b64_tr_b16 v[152:153], v185 offset:0x1400
	ds_read_b64_tr_b16 v[154:155], v185 offset:0x1c00
	s_waitcnt lgkmcnt(0)
	v_mfma_f32_32x32x16_bf16 v[96:111], v[176:179], v[148:151], v[96:111]
	v_mfma_f32_32x32x16_bf16 v[32:47], v[128:131], v[148:151], v[32:47]
	ds_read_b64_tr_b16 v[148:149], v185 offset:0x2400
	ds_read_b64_tr_b16 v[150:151], v185 offset:0x2c00
	v_mfma_f32_32x32x16_bf16 v[96:111], v[180:183], v[152:155], v[96:111]
	v_mfma_f32_32x32x16_bf16 v[32:47], v[132:135], v[152:155], v[32:47]
	ds_read_b64_tr_b16 v[152:153], v185 offset:0x3400
	ds_read_b64_tr_b16 v[154:155], v185 offset:0x3c00
	s_waitcnt lgkmcnt(0)
	v_mfma_f32_32x32x16_bf16 v[96:111], v[168:171], v[148:151], v[96:111]
	v_mfma_f32_32x32x16_bf16 v[32:47], v[136:139], v[148:151], v[32:47]
	ds_read_b64_tr_b16 v[148:149], v185 offset:0x600
	ds_read_b64_tr_b16 v[150:151], v185 offset:0xe00
	v_mfma_f32_32x32x16_bf16 v[96:111], v[172:175], v[152:155], v[96:111]
	v_mfma_f32_32x32x16_bf16 v[32:47], v[140:143], v[152:155], v[32:47]
	ds_read_b64_tr_b16 v[152:153], v185 offset:0x1600
	ds_read_b64_tr_b16 v[154:155], v185 offset:0x1e00
	s_waitcnt lgkmcnt(0)
	v_mfma_f32_32x32x16_bf16 v[112:127], v[176:179], v[148:151], v[112:127]
	v_mfma_f32_32x32x16_bf16 v[48:63], v[128:131], v[148:151], v[48:63]
	ds_read_b64_tr_b16 v[128:129], v185 offset:0x2600
	ds_read_b64_tr_b16 v[130:131], v185 offset:0x2e00
	ds_read_b64_tr_b16 v[148:149], v185 offset:0x3600
	ds_read_b64_tr_b16 v[150:151], v185 offset:0x3e00
	s_waitcnt lgkmcnt(0)
	v_mfma_f32_32x32x16_bf16 v[112:127], v[180:183], v[152:155], v[112:127]
	v_mfma_f32_32x32x16_bf16 v[48:63], v[132:135], v[152:155], v[48:63]
	v_mfma_f32_32x32x16_bf16 v[112:127], v[168:171], v[128:131], v[112:127]
	v_cmp_gt_u32_e32 vcc, 32, v228
	v_lshl_add_u32 v147, v226, 2, v184
	v_mfma_f32_32x32x16_bf16 v[48:63], v[136:139], v[128:131], v[48:63]
	v_mfma_f32_32x32x16_bf16 v[112:127], v[172:175], v[148:151], v[112:127]
	v_mfma_f32_32x32x16_bf16 v[48:63], v[140:143], v[148:151], v[48:63]
	s_and_saveexec_b64 s[6:7], vcc
	v_add_f32_e32 v128, v186, v187
	v_add_f32_e32 v128, v204, v128
	ds_write_b32 v147, v128
	s_or_b64 exec, exec, s[6:7]
	s_waitcnt lgkmcnt(0)
	v_add_u32_e32 v145, v184, v200
	ds_read_b128 v[128:131], v145
	ds_read_b128 v[132:135], v145 offset:32
	ds_read_b128 v[136:139], v145 offset:64
	ds_read_b128 v[140:143], v145 offset:96
	s_waitcnt lgkmcnt(0)
	s_mov_b64 s[6:7], exec
	s_and_b64 s[18:19], s[6:7], vcc
	v_mov_b32_e32 v206, 0x14000
	v_mov_b32_e32 v207, 0x68000
	v_mov_b32_e32 v208, 0x16000
	v_mov_b32_e32 v209, 0x66000
	v_mov_b32_e32 v210, 0x18000
	v_mov_b32_e32 v211, 0x64000
	v_mov_b32_e32 v212, 0x1a000
	v_mov_b32_e32 v213, 0x62000
	v_mov_b32_e32 v214, 0x1c000
	v_mov_b32_e32 v216, 0x60000
	v_mov_b32_e32 v218, 0x1e000
	v_mov_b32_e32 v219, 0x5e000
	v_mov_b32_e32 v220, 0x20000
	v_mov_b32_e32 v221, 0x5c000
	v_mov_b32_e32 v228, 0x22000
	v_mov_b32_e32 v230, 0x5a000
	v_mov_b32_e32 v231, 0x24000
	v_mov_b32_e32 v232, 0x58000
	v_mov_b32_e32 v233, 0x26000
	v_mov_b32_e32 v234, 0x56000
	v_mov_b32_e32 v235, 0x28000
	v_mov_b32_e32 v236, 0x54000
	v_mov_b32_e32 v237, 0x2a000
	v_mov_b32_e32 v238, 0x52000
	v_mov_b32_e32 v239, 0x2c000
	v_mov_b32_e32 v240, 0x50000
	v_mov_b32_e32 v241, 0x2e000
	v_mov_b32_e32 v242, 0x4e000
	v_mov_b32_e32 v243, 0x30000
	v_mov_b32_e32 v244, 0x4c000
	v_mov_b32_e32 v245, 0x32000
	v_mov_b32_e32 v246, 0x4a000
	v_mov_b32_e32 v247, 0x34000
	v_mov_b32_e32 v248, 0x48000
	v_mov_b32_e32 v249, 0x36000
	v_mov_b32_e32 v179, 0x46000
	v_mov_b32_e32 v181, 0x38000
	s_mov_b64 exec, s[18:19]
	s_cbranch_execz .LBB0_270
	v_add_f32_e32 v144, v144, v146
	v_add_f32_e32 v144, v205, v144
	ds_write_b32 v147, v144
	s_branch .LBB0_270
